# attention: s_setprio 1 around the LDS/MFMA half (QK^T reads..last P.V MFMA), 0 for the softmax half (segment priority for the pole half)
# speedup vs baseline: 1.0040x; 1.0040x over previous
.LBB0_371:
	v_lshrrev_b32_e32 v5, 2, v48
	v_and_b32_e32 v166, 12, v5
	v_mul_u32_u24_e32 v5, 0x120, v49
	v_add3_u32 v169, v24, 0, v5
	s_setprio 1
	ds_read_b128 v[24:27], v169 offset:0
	ds_read_b128 v[28:31], v169 offset:64
	ds_read_b128 v[32:35], v169 offset:0x80
	ds_read_b128 v[36:39], v169 offset:0xc0
	ds_read_b128 v[40:43], v169 offset:0x1200
	s_add_i32 s96, s96, s26
	v_sub_u32_e32 v5, v49, v166
	ds_read_b128 v[44:47], v169 offset:0x1240
	v_add_u32_e32 v5, s96, v5
	ds_read_b128 v[50:53], v169 offset:0x1280
	v_cvt_f32_i32_e32 v5, v5
	ds_read_b128 v[54:57], v169 offset:0x12c0
	s_waitcnt lgkmcnt(4)
	v_mfma_f32_16x16x32_bf16 v[24:27], v[24:27], v[12:15], 0
	v_mfma_f32_16x16x32_bf16 v[24:27], v[28:31], v[16:19], v[24:27]
	v_mfma_f32_16x16x32_bf16 v[24:27], v[32:35], v[20:23], v[24:27]
	ds_read_b128 v[32:35], v169 offset:0x2400
	v_mfma_f32_16x16x32_bf16 v[24:27], v[36:39], v[8:11], v[24:27]
	ds_read_b128 v[36:39], v169 offset:0x2440
	ds_read_b128 v[58:61], v169 offset:0x2480
	ds_read_b128 v[62:65], v169 offset:0x24c0
	s_waitcnt lgkmcnt(4)
	v_mfma_f32_16x16x32_bf16 v[28:31], v[40:43], v[12:15], 0
	ds_read_b128 v[40:43], v169 offset:0x3600
	v_mfma_f32_16x16x32_bf16 v[28:31], v[44:47], v[16:19], v[28:31]
	v_mfma_f32_16x16x32_bf16 v[28:31], v[50:53], v[20:23], v[28:31]
	ds_read_b128 v[50:53], v169 offset:0x3640
	v_mfma_f32_16x16x32_bf16 v[28:31], v[54:57], v[8:11], v[28:31]
	ds_read_b128 v[54:57], v169 offset:0x3680
	ds_read_b128 v[66:69], v169 offset:0x36c0
	s_waitcnt lgkmcnt(4)
	v_mfma_f32_16x16x32_bf16 v[32:35], v[32:35], v[12:15], 0
	s_waitcnt lgkmcnt(0)
	v_mfma_f32_16x16x32_bf16 v[32:35], v[36:39], v[16:19], v[32:35]
	v_mfma_f32_16x16x32_bf16 v[32:35], v[58:61], v[20:23], v[32:35]
	v_mfma_f32_16x16x32_bf16 v[32:35], v[62:65], v[8:11], v[32:35]
	v_mfma_f32_16x16x32_bf16 v[36:39], v[40:43], v[12:15], 0
	v_cvt_f32_u32_e32 v213, s2
	s_waitcnt lgkmcnt(0)
	s_barrier
	s_sub_i32 s14, s12, s2
	v_mfma_f32_16x16x32_bf16 v[36:39], v[50:53], v[16:19], v[36:39]
	v_sub_f32_e32 v46, v5, v213
	s_or_b32 s28, s2, 63
	v_add_f32_e32 v44, 0xc1800000, v46
	v_mfma_f32_16x16x32_bf16 v[36:39], v[54:57], v[20:23], v[36:39]
	v_add_f32_e32 v42, 0xc2000000, v46
	v_add_f32_e32 v40, 0xc2400000, v46
	s_mov_b64 s[2:3], -1
	v_mfma_f32_16x16x32_bf16 v[36:39], v[66:69], v[8:11], v[36:39]
	s_setprio 0
	s_cmp_lt_i32 s28, s96
	v_add_f32_e32 v47, -1.0, v46
	v_add_f32_e32 v45, -1.0, v44
	v_add_f32_e32 v43, -1.0, v42
	v_add_f32_e32 v41, -1.0, v40
	s_cbranch_scc1 .LBB0_375
	v_pk_add_f32 v[50:51], v[46:47], -2.0 op_sel_hi:[1,0]
	v_and_b32_e32 v52, 0x7fffffff, v46
	v_and_b32_e32 v51, 0x7fffffff, v51
	v_and_b32_e32 v50, 0x7fffffff, v50
	v_pk_fma_f32 v[114:115], v[50:51], v[146:147], v[26:27] op_sel_hi:[1,0,1]
	v_pk_add_f32 v[50:51], v[44:45], -2.0 op_sel_hi:[1,0]
	v_and_b32_e32 v53, 0x7fffffff, v47
	v_and_b32_e32 v51, 0x7fffffff, v51
	v_and_b32_e32 v50, 0x7fffffff, v50
	v_pk_fma_f32 v[118:119], v[50:51], v[146:147], v[30:31] op_sel_hi:[1,0,1]
	v_pk_add_f32 v[50:51], v[42:43], -2.0 op_sel_hi:[1,0]
	v_pk_fma_f32 v[112:113], v[52:53], v[146:147], v[24:25] op_sel_hi:[1,0,1]
	v_and_b32_e32 v52, 0x7fffffff, v44
	v_and_b32_e32 v53, 0x7fffffff, v45
	v_and_b32_e32 v51, 0x7fffffff, v51
	v_and_b32_e32 v50, 0x7fffffff, v50
	v_pk_fma_f32 v[116:117], v[52:53], v[146:147], v[28:29] op_sel_hi:[1,0,1]
	v_and_b32_e32 v52, 0x7fffffff, v42
	v_and_b32_e32 v53, 0x7fffffff, v43
	v_pk_fma_f32 v[122:123], v[50:51], v[146:147], v[34:35] op_sel_hi:[1,0,1]
	v_pk_add_f32 v[50:51], v[40:41], -2.0 op_sel_hi:[1,0]
	v_pk_fma_f32 v[120:121], v[52:53], v[146:147], v[32:33] op_sel_hi:[1,0,1]
	v_and_b32_e32 v51, 0x7fffffff, v51
	v_and_b32_e32 v50, 0x7fffffff, v50
	v_and_b32_e32 v52, 0x7fffffff, v40
	v_and_b32_e32 v53, 0x7fffffff, v41
	v_pk_fma_f32 v[126:127], v[50:51], v[146:147], v[38:39] op_sel_hi:[1,0,1]
	s_cmp_lt_i32 s14, 64
	v_pk_fma_f32 v[124:125], v[52:53], v[146:147], v[36:37] op_sel_hi:[1,0,1]
	s_cbranch_scc0 .LBB0_374
	v_or_b32_e32 v50, 1, v166
	v_cmp_gt_i32_e64 s[42:43], s14, v50
	v_or_b32_e32 v50, 2, v166
	v_cmp_gt_i32_e64 s[44:45], s14, v50
	v_or_b32_e32 v50, 3, v166
	v_cmp_gt_i32_e64 s[46:47], s14, v50
	s_or_b64 s[44:45], s[46:47], s[44:45]
	v_cmp_gt_i32_e32 vcc, s14, v166
	s_or_b64 s[42:43], s[44:45], s[42:43]
	s_or_b64 vcc, s[42:43], vcc
	v_or_b32_e32 v50, 16, v166
	v_cndmask_b32_e32 v112, v202, v112, vcc
	v_cmp_gt_i32_e32 vcc, s14, v50
	v_or_b32_e32 v50, 17, v166
	v_cndmask_b32_e64 v113, v202, v113, s[42:43]
	v_cmp_gt_i32_e64 s[42:43], s14, v50
	v_or_b32_e32 v50, 18, v166
	v_cndmask_b32_e64 v114, v202, v114, s[44:45]
	v_cmp_gt_i32_e64 s[44:45], s14, v50
	v_or_b32_e32 v50, 19, v166
	v_cndmask_b32_e64 v115, v202, v115, s[46:47]
	v_cmp_gt_i32_e64 s[46:47], s14, v50
	s_or_b64 s[44:45], s[46:47], s[44:45]
	s_or_b64 s[42:43], s[44:45], s[42:43]
	s_or_b64 vcc, s[42:43], vcc
	v_or_b32_e32 v50, 32, v166
	v_cndmask_b32_e32 v116, v202, v116, vcc
	v_cmp_gt_i32_e32 vcc, s14, v50
	v_or_b32_e32 v50, 33, v166
	v_cndmask_b32_e64 v117, v202, v117, s[42:43]
	v_cmp_gt_i32_e64 s[42:43], s14, v50
	v_or_b32_e32 v50, 34, v166
	v_cndmask_b32_e64 v118, v202, v118, s[44:45]
	v_cmp_gt_i32_e64 s[44:45], s14, v50
	v_or_b32_e32 v50, 35, v166
	v_cndmask_b32_e64 v119, v202, v119, s[46:47]
	v_cmp_gt_i32_e64 s[46:47], s14, v50
	s_or_b64 s[44:45], s[46:47], s[44:45]
	s_or_b64 s[42:43], s[44:45], s[42:43]
	s_or_b64 vcc, s[42:43], vcc
	v_or_b32_e32 v50, 48, v166
	v_cndmask_b32_e32 v120, v202, v120, vcc
	v_cmp_gt_i32_e32 vcc, s14, v50
	v_or_b32_e32 v50, 49, v166
	v_cndmask_b32_e64 v121, v202, v121, s[42:43]
	v_cmp_gt_i32_e64 s[42:43], s14, v50
	v_or_b32_e32 v50, 50, v166
	v_cndmask_b32_e64 v122, v202, v122, s[44:45]
	v_cmp_gt_i32_e64 s[44:45], s14, v50
	v_or_b32_e32 v50, 51, v166
	v_cndmask_b32_e64 v123, v202, v123, s[46:47]
	v_cmp_gt_i32_e64 s[46:47], s14, v50
	s_or_b64 s[44:45], s[46:47], s[44:45]
	s_or_b64 s[42:43], s[44:45], s[42:43]
	s_or_b64 vcc, s[42:43], vcc
	v_cndmask_b32_e64 v127, v202, v127, s[46:47]
	v_cndmask_b32_e64 v126, v202, v126, s[44:45]
	v_cndmask_b32_e64 v125, v202, v125, s[42:43]
	v_cndmask_b32_e32 v124, v202, v124, vcc

.LBB0_386:
	s_mul_i32 s7, s1, 0xd000
	s_mov_b32 s89, s1
	s_add_i32 s1, s7, 0
	s_add_i32 s2, s81, 0xffffff81
	v_add_u32_e32 v128, s1, v4
	s_ashr_i32 s3, s2, 31
	s_waitcnt lgkmcnt(0)
	s_barrier
	s_waitcnt vmcnt(5)
	ds_write_b128 v128, v[92:95]
	s_waitcnt vmcnt(4)
	ds_write_b128 v128, v[88:91] offset:128
	v_add_u32_e32 v88, s1, v178
	s_lshl_b64 s[2:3], s[2:3], 12
	s_waitcnt vmcnt(3)
	ds_write_b128 v88, v[96:99] offset:18432
	s_waitcnt vmcnt(2)
	ds_write_b128 v88, v[100:103] offset:18560
	s_waitcnt vmcnt(1)
	ds_write_b128 v88, v[104:107] offset:18688
	s_waitcnt vmcnt(0)
	ds_write_b128 v88, v[108:111] offset:18816
	v_lshl_add_u64 v[88:89], v[148:149], 0, s[2:3]
	v_lshl_add_u64 v[108:109], v[150:151], 0, s[2:3]
	global_load_dwordx4 v[92:95], v[88:89], off
	s_nop 0
	global_load_dwordx4 v[88:91], v[88:89], off offset:128
	s_nop 0
	global_load_dwordx4 v[96:99], v[108:109], off
	global_load_dwordx4 v[100:103], v[108:109], off offset:128
	global_load_dwordx4 v[104:107], v[108:109], off offset:256
	s_nop 0
	global_load_dwordx4 v[108:111], v[108:109], off offset:384
	s_mul_i32 s1, s55, 0xd000
	v_add_u32_e32 v147, s1, v169
	s_setprio 1
	ds_read_b128 v[128:131], v147 offset:0
	ds_read_b128 v[132:135], v147 offset:64
	ds_read_b128 v[136:139], v147 offset:0x80
	ds_read_b128 v[140:143], v147 offset:0xc0
	ds_read_b128 v[154:157], v147 offset:0x1200
	ds_read_b128 v[158:161], v147 offset:0x1240
	ds_read_b128 v[194:197], v147 offset:0x1280
	ds_read_b128 v[208:211], v147 offset:0x12c0
	s_waitcnt lgkmcnt(4)
	s_nop 0
	v_mfma_f32_16x16x32_bf16 v[128:131], v[128:131], v[12:15], 0
	v_mfma_f32_16x16x32_bf16 v[128:131], v[132:135], v[16:19], v[128:131]
	v_mfma_f32_16x16x32_bf16 v[128:131], v[136:139], v[20:23], v[128:131]
	ds_read_b128 v[136:139], v147 offset:0x2400
	v_mfma_f32_16x16x32_bf16 v[128:131], v[140:143], v[8:11], v[128:131]
	ds_read_b128 v[140:143], v147 offset:0x2440
	ds_read_b128 v[214:217], v147 offset:0x2480
	ds_read_b128 v[218:221], v147 offset:0x24c0
	s_waitcnt lgkmcnt(4)
	v_mfma_f32_16x16x32_bf16 v[132:135], v[154:157], v[12:15], 0
	ds_read_b128 v[154:157], v147 offset:0x3600
	v_mfma_f32_16x16x32_bf16 v[132:135], v[158:161], v[16:19], v[132:135]
	ds_read_b128 v[158:161], v147 offset:0x3640
	v_mfma_f32_16x16x32_bf16 v[132:135], v[194:197], v[20:23], v[132:135]
	ds_read_b128 v[194:197], v147 offset:0x3680
	v_mfma_f32_16x16x32_bf16 v[132:135], v[208:211], v[8:11], v[132:135]
	ds_read_b128 v[208:211], v147 offset:0x36c0
	s_waitcnt lgkmcnt(4)
	v_mfma_f32_16x16x32_bf16 v[136:139], v[136:139], v[12:15], 0
	s_waitcnt lgkmcnt(0)
	v_mfma_f32_16x16x32_bf16 v[136:139], v[140:143], v[16:19], v[136:139]
	v_mfma_f32_16x16x32_bf16 v[136:139], v[214:217], v[20:23], v[136:139]
	v_mfma_f32_16x16x32_bf16 v[140:143], v[218:221], v[8:11], v[136:139]
	v_mfma_f32_16x16x32_bf16 v[136:139], v[154:157], v[12:15], 0
	s_and_b64 vcc, exec, s[44:45]
	s_mul_i32 s27, s88, 0xd000
	v_mfma_f32_16x16x32_bf16 v[136:139], v[158:161], v[16:19], v[136:139]
	v_mfma_f32_16x16x32_bf16 v[136:139], v[194:197], v[20:23], v[136:139]
	v_mfma_f32_16x16x32_bf16 v[136:139], v[208:211], v[8:11], v[136:139]
	s_cbranch_vccnz .LBB0_388
	s_mul_i32 s2, s88, 0xd000
	v_add_u32_e32 v147, s2, v167
	v_cvt_pk_bf16_f32 v112, v112, v113
	v_cvt_pk_bf16_f32 v113, v114, v115
	v_cvt_pk_bf16_f32 v114, v116, v117
	v_cvt_pk_bf16_f32 v115, v118, v119
	v_cvt_pk_bf16_f32 v116, v120, v121
	v_cvt_pk_bf16_f32 v117, v122, v123
	v_cvt_pk_bf16_f32 v118, v124, v125
	v_cvt_pk_bf16_f32 v119, v126, v127
	ds_read_b64_tr_b16 v[120:121], v147 offset:0
	ds_read_b64_tr_b16 v[122:123], v147 offset:0x2200
	ds_read_b64_tr_b16 v[124:125], v147 offset:0x4400
	ds_read_b64_tr_b16 v[126:127], v147 offset:0x6600
	ds_read_b64_tr_b16 v[154:155], v147 offset:32
	ds_read_b64_tr_b16 v[156:157], v147 offset:0x2220
	ds_read_b64_tr_b16 v[158:159], v147 offset:0x4420
	ds_read_b64_tr_b16 v[160:161], v147 offset:0x6620
	ds_read_b64_tr_b16 v[194:195], v147 offset:64
	ds_read_b64_tr_b16 v[196:197], v147 offset:0x2240
	ds_read_b64_tr_b16 v[208:209], v147 offset:0x4440
	ds_read_b64_tr_b16 v[210:211], v147 offset:0x6640
	ds_read_b64_tr_b16 v[214:215], v147 offset:0x60
	ds_read_b64_tr_b16 v[216:217], v147 offset:0x2260
	ds_read_b64_tr_b16 v[218:219], v147 offset:0x4460
	ds_read_b64_tr_b16 v[220:221], v147 offset:0x6660
	s_waitcnt lgkmcnt(8)
	s_nop 0
	v_mfma_f32_16x16x32_bf16 v[84:87], v[112:115], v[120:123], v[84:87]
	ds_read_b64_tr_b16 v[120:121], v147 offset:0x80
	ds_read_b64_tr_b16 v[122:123], v147 offset:0x2280
	v_mfma_f32_16x16x32_bf16 v[84:87], v[116:119], v[124:127], v[84:87]
	ds_read_b64_tr_b16 v[124:125], v147 offset:0x4480
	ds_read_b64_tr_b16 v[126:127], v147 offset:0x6680
	v_mfma_f32_16x16x32_bf16 v[80:83], v[112:115], v[154:157], v[80:83]
	ds_read_b64_tr_b16 v[154:155], v147 offset:0xa0
	ds_read_b64_tr_b16 v[156:157], v147 offset:0x22a0
	v_mfma_f32_16x16x32_bf16 v[80:83], v[116:119], v[158:161], v[80:83]
	ds_read_b64_tr_b16 v[158:159], v147 offset:0x44a0
	ds_read_b64_tr_b16 v[160:161], v147 offset:0x66a0
	s_waitcnt lgkmcnt(8)
	v_mfma_f32_16x16x32_bf16 v[76:79], v[112:115], v[194:197], v[76:79]
	ds_read_b64_tr_b16 v[194:195], v147 offset:0xc0
	ds_read_b64_tr_b16 v[196:197], v147 offset:0x22c0
	v_mfma_f32_16x16x32_bf16 v[76:79], v[116:119], v[208:211], v[76:79]
	ds_read_b64_tr_b16 v[208:209], v147 offset:0x44c0
	ds_read_b64_tr_b16 v[210:211], v147 offset:0x66c0
	v_mfma_f32_16x16x32_bf16 v[72:75], v[112:115], v[214:217], v[72:75]
	ds_read_b64_tr_b16 v[214:215], v147 offset:0xe0
	ds_read_b64_tr_b16 v[216:217], v147 offset:0x22e0
	v_mfma_f32_16x16x32_bf16 v[72:75], v[116:119], v[218:221], v[72:75]
	ds_read_b64_tr_b16 v[218:219], v147 offset:0x44e0
	ds_read_b64_tr_b16 v[220:221], v147 offset:0x66e0
	s_waitcnt lgkmcnt(8)
	v_mfma_f32_16x16x32_bf16 v[68:71], v[112:115], v[120:123], v[68:71]
	ds_read_b64_tr_b16 v[120:121], v147 offset:0x100
	ds_read_b64_tr_b16 v[122:123], v147 offset:0x2300
	v_mfma_f32_16x16x32_bf16 v[68:71], v[116:119], v[124:127], v[68:71]
	ds_read_b64_tr_b16 v[124:125], v147 offset:0x4500
	ds_read_b64_tr_b16 v[126:127], v147 offset:0x6700
	v_mfma_f32_16x16x32_bf16 v[64:67], v[112:115], v[154:157], v[64:67]
	ds_read_b64_tr_b16 v[154:155], v147 offset:0x120
	ds_read_b64_tr_b16 v[156:157], v147 offset:0x2320
	v_mfma_f32_16x16x32_bf16 v[64:67], v[116:119], v[158:161], v[64:67]
	ds_read_b64_tr_b16 v[158:159], v147 offset:0x4520
	ds_read_b64_tr_b16 v[160:161], v147 offset:0x6720
	s_waitcnt lgkmcnt(8)
	v_mfma_f32_16x16x32_bf16 v[60:63], v[112:115], v[194:197], v[60:63]
	ds_read_b64_tr_b16 v[194:195], v147 offset:0x140
	ds_read_b64_tr_b16 v[196:197], v147 offset:0x2340
	v_mfma_f32_16x16x32_bf16 v[60:63], v[116:119], v[208:211], v[60:63]
	ds_read_b64_tr_b16 v[208:209], v147 offset:0x4540
	ds_read_b64_tr_b16 v[210:211], v147 offset:0x6740
	v_mfma_f32_16x16x32_bf16 v[56:59], v[112:115], v[214:217], v[56:59]
	ds_read_b64_tr_b16 v[214:215], v147 offset:0x160
	ds_read_b64_tr_b16 v[216:217], v147 offset:0x2360
	v_mfma_f32_16x16x32_bf16 v[56:59], v[116:119], v[218:221], v[56:59]
	ds_read_b64_tr_b16 v[218:219], v147 offset:0x4560
	ds_read_b64_tr_b16 v[220:221], v147 offset:0x6760
	s_waitcnt lgkmcnt(8)
	v_mfma_f32_16x16x32_bf16 v[48:51], v[112:115], v[120:123], v[48:51]
	ds_read_b64_tr_b16 v[120:121], v147 offset:0x180
	ds_read_b64_tr_b16 v[122:123], v147 offset:0x2380
	v_mfma_f32_16x16x32_bf16 v[48:51], v[116:119], v[124:127], v[48:51]
	ds_read_b64_tr_b16 v[124:125], v147 offset:0x4580
	ds_read_b64_tr_b16 v[126:127], v147 offset:0x6780
	v_mfma_f32_16x16x32_bf16 v[40:43], v[112:115], v[154:157], v[40:43]
	ds_read_b64_tr_b16 v[154:155], v147 offset:0x1a0
	ds_read_b64_tr_b16 v[156:157], v147 offset:0x23a0
	v_mfma_f32_16x16x32_bf16 v[40:43], v[116:119], v[158:161], v[40:43]
	ds_read_b64_tr_b16 v[158:159], v147 offset:0x45a0
	ds_read_b64_tr_b16 v[160:161], v147 offset:0x67a0
	s_waitcnt lgkmcnt(8)
	v_mfma_f32_16x16x32_bf16 v[36:39], v[112:115], v[194:197], v[36:39]
	ds_read_b64_tr_b16 v[194:195], v147 offset:0x1c0
	ds_read_b64_tr_b16 v[196:197], v147 offset:0x23c0
	v_mfma_f32_16x16x32_bf16 v[36:39], v[116:119], v[208:211], v[36:39]
	ds_read_b64_tr_b16 v[208:209], v147 offset:0x45c0
	ds_read_b64_tr_b16 v[210:211], v147 offset:0x67c0
	v_mfma_f32_16x16x32_bf16 v[28:31], v[112:115], v[214:217], v[28:31]
	ds_read_b64_tr_b16 v[214:215], v147 offset:0x1e0
	ds_read_b64_tr_b16 v[216:217], v147 offset:0x23e0
	v_mfma_f32_16x16x32_bf16 v[28:31], v[116:119], v[218:221], v[28:31]
	ds_read_b64_tr_b16 v[218:219], v147 offset:0x45e0
	ds_read_b64_tr_b16 v[220:221], v147 offset:0x67e0
	s_waitcnt lgkmcnt(8)
	v_mfma_f32_16x16x32_bf16 v[44:47], v[112:115], v[120:123], v[44:47]
	s_waitcnt lgkmcnt(0)
	v_mfma_f32_16x16x32_bf16 v[52:55], v[112:115], v[154:157], v[52:55]
	v_mfma_f32_16x16x32_bf16 v[44:47], v[116:119], v[124:127], v[44:47]
	v_mfma_f32_16x16x32_bf16 v[52:55], v[116:119], v[158:161], v[52:55]
	v_mfma_f32_16x16x32_bf16 v[32:35], v[112:115], v[194:197], v[32:35]
	v_mfma_f32_16x16x32_bf16 v[24:27], v[112:115], v[214:217], v[24:27]
	v_mfma_f32_16x16x32_bf16 v[32:35], v[116:119], v[208:211], v[32:35]
	v_mfma_f32_16x16x32_bf16 v[24:27], v[116:119], v[218:221], v[24:27]
	s_setprio 0
.LBB0_388:
	s_setprio 0
	s_add_i32 s2, s81, 1
	v_cvt_f32_i32_e32 v112, s2
	s_waitcnt lgkmcnt(0)
	s_barrier
	s_add_i32 s4, s81, 64
	s_mov_b64 s[2:3], -1
	v_sub_f32_e32 v160, v5, v112
	v_add_f32_e32 v158, 0xc1800000, v160
	v_add_f32_e32 v156, 0xc2000000, v160
	v_add_f32_e32 v154, 0xc2400000, v160
	s_cmp_lt_i32 s4, s96
	v_add_f32_e32 v161, -1.0, v160
	v_add_f32_e32 v159, -1.0, v158
	v_add_f32_e32 v157, -1.0, v156
	v_add_f32_e32 v155, -1.0, v154
	s_cbranch_scc1 .LBB0_392
	v_pk_add_f32 v[116:117], v[158:159], -2.0 op_sel_hi:[1,0]
	v_mov_b32_e32 v147, v146
	v_and_b32_e32 v117, 0x7fffffff, v117
	v_and_b32_e32 v116, 0x7fffffff, v116
	v_and_b32_e32 v120, 0x7fffffff, v158
	v_and_b32_e32 v121, 0x7fffffff, v159
	v_pk_fma_f32 v[118:119], v[116:117], v[146:147], v[134:135]
	v_pk_fma_f32 v[116:117], v[120:121], v[152:153], v[132:133]
	v_pk_add_f32 v[120:121], v[156:157], -2.0 op_sel_hi:[1,0]
	v_and_b32_e32 v124, 0x7fffffff, v156
	v_and_b32_e32 v121, 0x7fffffff, v121
	v_and_b32_e32 v120, 0x7fffffff, v120
	v_and_b32_e32 v125, 0x7fffffff, v157
	v_pk_add_f32 v[112:113], v[160:161], -2.0 op_sel_hi:[1,0]
	v_pk_fma_f32 v[122:123], v[120:121], v[146:147], v[142:143]
	v_pk_fma_f32 v[120:121], v[124:125], v[152:153], v[140:141]
	v_pk_add_f32 v[124:125], v[154:155], -2.0 op_sel_hi:[1,0]
	s_sub_i32 s2, s86, 64
	v_and_b32_e32 v115, 0x7fffffff, v113
	v_and_b32_e32 v114, 0x7fffffff, v112
	v_and_b32_e32 v112, 0x7fffffff, v160
	v_and_b32_e32 v113, 0x7fffffff, v161
	v_and_b32_e32 v125, 0x7fffffff, v125
	v_and_b32_e32 v124, 0x7fffffff, v124
	v_and_b32_e32 v194, 0x7fffffff, v154
	v_and_b32_e32 v195, 0x7fffffff, v155
	v_pk_fma_f32 v[112:113], v[112:113], v[152:153], v[128:129]
	v_pk_fma_f32 v[114:115], v[114:115], v[146:147], v[130:131]
	v_pk_fma_f32 v[126:127], v[124:125], v[146:147], v[138:139]
	s_cmp_lt_i32 s2, 64
	v_pk_fma_f32 v[124:125], v[194:195], v[152:153], v[136:137]
	s_cbranch_scc0 .LBB0_391
	v_cmp_gt_i32_e64 s[46:47], s2, v179
	v_cmp_gt_i32_e64 s[48:49], s2, v180
	v_cmp_gt_i32_e64 s[44:45], s2, v2
	s_or_b64 s[46:47], s[48:49], s[46:47]
	v_cmp_gt_i32_e32 vcc, s2, v166
	v_cndmask_b32_e64 v115, v202, v115, s[48:49]
	v_cndmask_b32_e64 v114, v202, v114, s[46:47]
	s_or_b64 s[44:45], s[46:47], s[44:45]
	v_cmp_gt_i32_e64 s[46:47], s2, v183
	v_cmp_gt_i32_e64 s[48:49], s2, v184
	v_cndmask_b32_e64 v113, v202, v113, s[44:45]
	s_or_b64 vcc, s[44:45], vcc
	v_cmp_gt_i32_e64 s[44:45], s2, v182
	s_or_b64 s[46:47], s[48:49], s[46:47]
	v_cndmask_b32_e32 v112, v202, v112, vcc
	v_cmp_gt_i32_e32 vcc, s2, v181
	v_cndmask_b32_e64 v119, v202, v119, s[48:49]
	v_cndmask_b32_e64 v118, v202, v118, s[46:47]
	s_or_b64 s[44:45], s[46:47], s[44:45]
	v_cmp_gt_i32_e64 s[46:47], s2, v187
	v_cmp_gt_i32_e64 s[48:49], s2, v188
	v_cndmask_b32_e64 v117, v202, v117, s[44:45]
	s_or_b64 vcc, s[44:45], vcc
	v_cmp_gt_i32_e64 s[44:45], s2, v186
	s_or_b64 s[46:47], s[48:49], s[46:47]
	v_cndmask_b32_e32 v116, v202, v116, vcc
	v_cmp_gt_i32_e32 vcc, s2, v185
	v_cndmask_b32_e64 v123, v202, v123, s[48:49]
	v_cndmask_b32_e64 v122, v202, v122, s[46:47]
	s_or_b64 s[44:45], s[46:47], s[44:45]
	v_cmp_gt_i32_e64 s[46:47], s2, v191
	v_cmp_gt_i32_e64 s[48:49], s2, v192
	v_cndmask_b32_e64 v121, v202, v121, s[44:45]
	s_or_b64 vcc, s[44:45], vcc
	v_cmp_gt_i32_e64 s[44:45], s2, v190
	s_or_b64 s[46:47], s[48:49], s[46:47]
	v_cndmask_b32_e32 v120, v202, v120, vcc
	v_cmp_gt_i32_e32 vcc, s2, v189
	s_or_b64 s[44:45], s[46:47], s[44:45]
	s_or_b64 vcc, s[44:45], vcc
	v_cndmask_b32_e64 v127, v202, v127, s[48:49]
	v_cndmask_b32_e64 v126, v202, v126, s[46:47]
	v_cndmask_b32_e64 v125, v202, v125, s[44:45]
	v_cndmask_b32_e32 v124, v202, v124, vcc

.LBB0_402:
	v_add_u32_e32 v147, s7, v169
	s_setprio 1
	ds_read_b128 v[128:131], v147 offset:0
	ds_read_b128 v[132:135], v147 offset:64
	ds_read_b128 v[136:139], v147 offset:0x80
	ds_read_b128 v[140:143], v147 offset:0xc0
	ds_read_b128 v[154:157], v147 offset:0x1200
	ds_read_b128 v[158:161], v147 offset:0x1240
	ds_read_b128 v[194:197], v147 offset:0x1280
	ds_read_b128 v[208:211], v147 offset:0x12c0
	s_waitcnt lgkmcnt(4)
	s_nop 0
	v_mfma_f32_16x16x32_bf16 v[128:131], v[128:131], v[12:15], 0
	v_mfma_f32_16x16x32_bf16 v[128:131], v[132:135], v[16:19], v[128:131]
	v_mfma_f32_16x16x32_bf16 v[128:131], v[136:139], v[20:23], v[128:131]
	ds_read_b128 v[136:139], v147 offset:0x2400
	v_mfma_f32_16x16x32_bf16 v[128:131], v[140:143], v[8:11], v[128:131]
	ds_read_b128 v[140:143], v147 offset:0x2440
	ds_read_b128 v[214:217], v147 offset:0x2480
	ds_read_b128 v[218:221], v147 offset:0x24c0
	s_waitcnt lgkmcnt(4)
	v_mfma_f32_16x16x32_bf16 v[132:135], v[154:157], v[12:15], 0
	ds_read_b128 v[154:157], v147 offset:0x3600
	v_mfma_f32_16x16x32_bf16 v[132:135], v[158:161], v[16:19], v[132:135]
	ds_read_b128 v[158:161], v147 offset:0x3640
	v_mfma_f32_16x16x32_bf16 v[132:135], v[194:197], v[20:23], v[132:135]
	ds_read_b128 v[194:197], v147 offset:0x3680
	v_mfma_f32_16x16x32_bf16 v[132:135], v[208:211], v[8:11], v[132:135]
	ds_read_b128 v[208:211], v147 offset:0x36c0
	s_waitcnt lgkmcnt(4)
	v_mfma_f32_16x16x32_bf16 v[136:139], v[136:139], v[12:15], 0
	s_waitcnt lgkmcnt(0)
	v_mfma_f32_16x16x32_bf16 v[136:139], v[140:143], v[16:19], v[136:139]
	v_mfma_f32_16x16x32_bf16 v[136:139], v[214:217], v[20:23], v[136:139]
	v_mfma_f32_16x16x32_bf16 v[140:143], v[218:221], v[8:11], v[136:139]
	v_mfma_f32_16x16x32_bf16 v[136:139], v[154:157], v[12:15], 0
	s_andn2_b64 vcc, exec, s[4:5]
	v_mfma_f32_16x16x32_bf16 v[136:139], v[158:161], v[16:19], v[136:139]
	v_mfma_f32_16x16x32_bf16 v[136:139], v[194:197], v[20:23], v[136:139]
	v_mfma_f32_16x16x32_bf16 v[136:139], v[208:211], v[8:11], v[136:139]
	s_cbranch_vccnz .LBB0_404
	v_add_u32_e32 v147, s1, v167
	v_cvt_pk_bf16_f32 v112, v112, v113
	v_cvt_pk_bf16_f32 v113, v114, v115
	v_cvt_pk_bf16_f32 v114, v116, v117
	v_cvt_pk_bf16_f32 v115, v118, v119
	v_cvt_pk_bf16_f32 v116, v120, v121
	v_cvt_pk_bf16_f32 v117, v122, v123
	v_cvt_pk_bf16_f32 v118, v124, v125
	v_cvt_pk_bf16_f32 v119, v126, v127
	ds_read_b64_tr_b16 v[120:121], v147 offset:0
	ds_read_b64_tr_b16 v[122:123], v147 offset:0x2200
	ds_read_b64_tr_b16 v[124:125], v147 offset:0x4400
	ds_read_b64_tr_b16 v[126:127], v147 offset:0x6600
	ds_read_b64_tr_b16 v[154:155], v147 offset:32
	ds_read_b64_tr_b16 v[156:157], v147 offset:0x2220
	ds_read_b64_tr_b16 v[158:159], v147 offset:0x4420
	ds_read_b64_tr_b16 v[160:161], v147 offset:0x6620
	ds_read_b64_tr_b16 v[194:195], v147 offset:64
	ds_read_b64_tr_b16 v[196:197], v147 offset:0x2240
	ds_read_b64_tr_b16 v[208:209], v147 offset:0x4440
	ds_read_b64_tr_b16 v[210:211], v147 offset:0x6640
	ds_read_b64_tr_b16 v[214:215], v147 offset:0x60
	ds_read_b64_tr_b16 v[216:217], v147 offset:0x2260
	ds_read_b64_tr_b16 v[218:219], v147 offset:0x4460
	ds_read_b64_tr_b16 v[220:221], v147 offset:0x6660
	s_waitcnt lgkmcnt(8)
	s_nop 0
	v_mfma_f32_16x16x32_bf16 v[84:87], v[112:115], v[120:123], v[84:87]
	ds_read_b64_tr_b16 v[120:121], v147 offset:0x80
	ds_read_b64_tr_b16 v[122:123], v147 offset:0x2280
	v_mfma_f32_16x16x32_bf16 v[84:87], v[116:119], v[124:127], v[84:87]
	ds_read_b64_tr_b16 v[124:125], v147 offset:0x4480
	ds_read_b64_tr_b16 v[126:127], v147 offset:0x6680
	v_mfma_f32_16x16x32_bf16 v[80:83], v[112:115], v[154:157], v[80:83]
	ds_read_b64_tr_b16 v[154:155], v147 offset:0xa0
	ds_read_b64_tr_b16 v[156:157], v147 offset:0x22a0
	v_mfma_f32_16x16x32_bf16 v[80:83], v[116:119], v[158:161], v[80:83]
	ds_read_b64_tr_b16 v[158:159], v147 offset:0x44a0
	ds_read_b64_tr_b16 v[160:161], v147 offset:0x66a0
	s_waitcnt lgkmcnt(8)
	v_mfma_f32_16x16x32_bf16 v[76:79], v[112:115], v[194:197], v[76:79]
	ds_read_b64_tr_b16 v[194:195], v147 offset:0xc0
	ds_read_b64_tr_b16 v[196:197], v147 offset:0x22c0
	v_mfma_f32_16x16x32_bf16 v[76:79], v[116:119], v[208:211], v[76:79]
	ds_read_b64_tr_b16 v[208:209], v147 offset:0x44c0
	ds_read_b64_tr_b16 v[210:211], v147 offset:0x66c0
	v_mfma_f32_16x16x32_bf16 v[72:75], v[112:115], v[214:217], v[72:75]
	ds_read_b64_tr_b16 v[214:215], v147 offset:0xe0
	ds_read_b64_tr_b16 v[216:217], v147 offset:0x22e0
	v_mfma_f32_16x16x32_bf16 v[72:75], v[116:119], v[218:221], v[72:75]
	ds_read_b64_tr_b16 v[218:219], v147 offset:0x44e0
	ds_read_b64_tr_b16 v[220:221], v147 offset:0x66e0
	s_waitcnt lgkmcnt(8)
	v_mfma_f32_16x16x32_bf16 v[68:71], v[112:115], v[120:123], v[68:71]
	ds_read_b64_tr_b16 v[120:121], v147 offset:0x100
	ds_read_b64_tr_b16 v[122:123], v147 offset:0x2300
	v_mfma_f32_16x16x32_bf16 v[68:71], v[116:119], v[124:127], v[68:71]
	ds_read_b64_tr_b16 v[124:125], v147 offset:0x4500
	ds_read_b64_tr_b16 v[126:127], v147 offset:0x6700
	v_mfma_f32_16x16x32_bf16 v[64:67], v[112:115], v[154:157], v[64:67]
	ds_read_b64_tr_b16 v[154:155], v147 offset:0x120
	ds_read_b64_tr_b16 v[156:157], v147 offset:0x2320
	v_mfma_f32_16x16x32_bf16 v[64:67], v[116:119], v[158:161], v[64:67]
	ds_read_b64_tr_b16 v[158:159], v147 offset:0x4520
	ds_read_b64_tr_b16 v[160:161], v147 offset:0x6720
	s_waitcnt lgkmcnt(8)
	v_mfma_f32_16x16x32_bf16 v[60:63], v[112:115], v[194:197], v[60:63]
	ds_read_b64_tr_b16 v[194:195], v147 offset:0x140
	ds_read_b64_tr_b16 v[196:197], v147 offset:0x2340
	v_mfma_f32_16x16x32_bf16 v[60:63], v[116:119], v[208:211], v[60:63]
	ds_read_b64_tr_b16 v[208:209], v147 offset:0x4540
	ds_read_b64_tr_b16 v[210:211], v147 offset:0x6740
	v_mfma_f32_16x16x32_bf16 v[56:59], v[112:115], v[214:217], v[56:59]
	ds_read_b64_tr_b16 v[214:215], v147 offset:0x160
	ds_read_b64_tr_b16 v[216:217], v147 offset:0x2360
	v_mfma_f32_16x16x32_bf16 v[56:59], v[116:119], v[218:221], v[56:59]
	ds_read_b64_tr_b16 v[218:219], v147 offset:0x4560
	ds_read_b64_tr_b16 v[220:221], v147 offset:0x6760
	s_waitcnt lgkmcnt(8)
	v_mfma_f32_16x16x32_bf16 v[48:51], v[112:115], v[120:123], v[48:51]
	ds_read_b64_tr_b16 v[120:121], v147 offset:0x180
	ds_read_b64_tr_b16 v[122:123], v147 offset:0x2380
	v_mfma_f32_16x16x32_bf16 v[48:51], v[116:119], v[124:127], v[48:51]
	ds_read_b64_tr_b16 v[124:125], v147 offset:0x4580
	ds_read_b64_tr_b16 v[126:127], v147 offset:0x6780
	v_mfma_f32_16x16x32_bf16 v[40:43], v[112:115], v[154:157], v[40:43]
	ds_read_b64_tr_b16 v[154:155], v147 offset:0x1a0
	ds_read_b64_tr_b16 v[156:157], v147 offset:0x23a0
	v_mfma_f32_16x16x32_bf16 v[40:43], v[116:119], v[158:161], v[40:43]
	ds_read_b64_tr_b16 v[158:159], v147 offset:0x45a0
	ds_read_b64_tr_b16 v[160:161], v147 offset:0x67a0
	s_waitcnt lgkmcnt(8)
	v_mfma_f32_16x16x32_bf16 v[36:39], v[112:115], v[194:197], v[36:39]
	ds_read_b64_tr_b16 v[194:195], v147 offset:0x1c0
	ds_read_b64_tr_b16 v[196:197], v147 offset:0x23c0
	v_mfma_f32_16x16x32_bf16 v[36:39], v[116:119], v[208:211], v[36:39]
	ds_read_b64_tr_b16 v[208:209], v147 offset:0x45c0
	ds_read_b64_tr_b16 v[210:211], v147 offset:0x67c0
	v_mfma_f32_16x16x32_bf16 v[28:31], v[112:115], v[214:217], v[28:31]
	ds_read_b64_tr_b16 v[214:215], v147 offset:0x1e0
	ds_read_b64_tr_b16 v[216:217], v147 offset:0x23e0
	v_mfma_f32_16x16x32_bf16 v[28:31], v[116:119], v[218:221], v[28:31]
	ds_read_b64_tr_b16 v[218:219], v147 offset:0x45e0
	ds_read_b64_tr_b16 v[220:221], v147 offset:0x67e0
	s_waitcnt lgkmcnt(8)
	v_mfma_f32_16x16x32_bf16 v[44:47], v[112:115], v[120:123], v[44:47]
	s_waitcnt lgkmcnt(0)
	v_mfma_f32_16x16x32_bf16 v[52:55], v[112:115], v[154:157], v[52:55]
	v_mfma_f32_16x16x32_bf16 v[44:47], v[116:119], v[124:127], v[44:47]
	v_mfma_f32_16x16x32_bf16 v[52:55], v[116:119], v[158:161], v[52:55]
	v_mfma_f32_16x16x32_bf16 v[32:35], v[112:115], v[194:197], v[32:35]
	v_mfma_f32_16x16x32_bf16 v[24:27], v[112:115], v[214:217], v[24:27]
	v_mfma_f32_16x16x32_bf16 v[32:35], v[116:119], v[208:211], v[32:35]
	v_mfma_f32_16x16x32_bf16 v[24:27], v[116:119], v[218:221], v[24:27]
	s_setprio 0
.LBB0_404:
	s_setprio 0
	s_sub_i32 s1, s81, 63
	v_cvt_f32_i32_e32 v112, s1
	s_waitcnt lgkmcnt(0)
	s_barrier
	s_mov_b64 s[4:5], -1
	s_cmp_lt_i32 s81, s96
	v_sub_f32_e32 v160, v5, v112
	v_add_f32_e32 v158, 0xc1800000, v160
	v_add_f32_e32 v156, 0xc2000000, v160
	v_add_f32_e32 v154, 0xc2400000, v160
	v_add_f32_e32 v161, -1.0, v160
	v_add_f32_e32 v159, -1.0, v158
	v_add_f32_e32 v157, -1.0, v156
	v_add_f32_e32 v155, -1.0, v154
	s_cbranch_scc1 .LBB0_408
	v_pk_add_f32 v[116:117], v[158:159], -2.0 op_sel_hi:[1,0]
	v_mov_b32_e32 v147, v146
	v_and_b32_e32 v117, 0x7fffffff, v117
	v_and_b32_e32 v116, 0x7fffffff, v116
	v_and_b32_e32 v120, 0x7fffffff, v158
	v_and_b32_e32 v121, 0x7fffffff, v159
	v_pk_fma_f32 v[118:119], v[116:117], v[146:147], v[134:135]
	v_pk_fma_f32 v[116:117], v[120:121], v[152:153], v[132:133]
	v_pk_add_f32 v[120:121], v[156:157], -2.0 op_sel_hi:[1,0]
	v_and_b32_e32 v124, 0x7fffffff, v156
	v_and_b32_e32 v121, 0x7fffffff, v121
	v_and_b32_e32 v120, 0x7fffffff, v120
	v_and_b32_e32 v125, 0x7fffffff, v157
	v_pk_add_f32 v[112:113], v[160:161], -2.0 op_sel_hi:[1,0]
	v_pk_fma_f32 v[122:123], v[120:121], v[146:147], v[142:143]
	v_pk_fma_f32 v[120:121], v[124:125], v[152:153], v[140:141]
	v_pk_add_f32 v[124:125], v[154:155], -2.0 op_sel_hi:[1,0]
	v_and_b32_e32 v115, 0x7fffffff, v113
	v_and_b32_e32 v114, 0x7fffffff, v112
	v_and_b32_e32 v112, 0x7fffffff, v160
	v_and_b32_e32 v113, 0x7fffffff, v161
	v_and_b32_e32 v125, 0x7fffffff, v125
	v_and_b32_e32 v124, 0x7fffffff, v124
	v_and_b32_e32 v194, 0x7fffffff, v154
	v_and_b32_e32 v195, 0x7fffffff, v155
	v_pk_fma_f32 v[112:113], v[112:113], v[152:153], v[128:129]
	v_pk_fma_f32 v[114:115], v[114:115], v[146:147], v[130:131]
	v_pk_fma_f32 v[126:127], v[124:125], v[146:147], v[138:139]
	s_cmp_lt_i32 s86, 64
	v_pk_fma_f32 v[124:125], v[194:195], v[152:153], v[136:137]
	s_cbranch_scc0 .LBB0_407
	v_cmp_gt_i32_e64 s[46:47], s86, v179
	v_cmp_gt_i32_e64 s[48:49], s86, v180
	v_cmp_gt_i32_e64 s[44:45], s86, v2
	s_or_b64 s[46:47], s[48:49], s[46:47]
	v_cmp_gt_i32_e32 vcc, s86, v166
	v_cndmask_b32_e64 v115, v202, v115, s[48:49]
	v_cndmask_b32_e64 v114, v202, v114, s[46:47]
	s_or_b64 s[44:45], s[46:47], s[44:45]
	v_cmp_gt_i32_e64 s[46:47], s86, v183
	v_cmp_gt_i32_e64 s[48:49], s86, v184
	v_cndmask_b32_e64 v113, v202, v113, s[44:45]
	s_or_b64 vcc, s[44:45], vcc
	v_cmp_gt_i32_e64 s[44:45], s86, v182
	s_or_b64 s[46:47], s[48:49], s[46:47]
	v_cndmask_b32_e32 v112, v202, v112, vcc
	v_cmp_gt_i32_e32 vcc, s86, v181
	v_cndmask_b32_e64 v119, v202, v119, s[48:49]
	v_cndmask_b32_e64 v118, v202, v118, s[46:47]
	s_or_b64 s[44:45], s[46:47], s[44:45]
	v_cmp_gt_i32_e64 s[46:47], s86, v187
	v_cmp_gt_i32_e64 s[48:49], s86, v188
	v_cndmask_b32_e64 v117, v202, v117, s[44:45]
	s_or_b64 vcc, s[44:45], vcc
	v_cmp_gt_i32_e64 s[44:45], s86, v186
	s_or_b64 s[46:47], s[48:49], s[46:47]
	v_cndmask_b32_e32 v116, v202, v116, vcc
	v_cmp_gt_i32_e32 vcc, s86, v185
	v_cndmask_b32_e64 v123, v202, v123, s[48:49]
	v_cndmask_b32_e64 v122, v202, v122, s[46:47]
	s_or_b64 s[44:45], s[46:47], s[44:45]
	v_cmp_gt_i32_e64 s[46:47], s86, v191
	v_cmp_gt_i32_e64 s[48:49], s86, v192
	v_cndmask_b32_e64 v121, v202, v121, s[44:45]
	s_or_b64 vcc, s[44:45], vcc
	v_cmp_gt_i32_e64 s[44:45], s86, v190
	s_or_b64 s[46:47], s[48:49], s[46:47]
	v_cndmask_b32_e32 v120, v202, v120, vcc
	v_cmp_gt_i32_e32 vcc, s86, v189
	s_or_b64 s[44:45], s[46:47], s[44:45]
	s_or_b64 vcc, s[44:45], vcc
	v_cndmask_b32_e64 v127, v202, v127, s[48:49]
	v_cndmask_b32_e64 v126, v202, v126, s[46:47]
	v_cndmask_b32_e64 v125, v202, v125, s[44:45]
	v_cndmask_b32_e32 v124, v202, v124, vcc

.LBB0_420:
	s_waitcnt lgkmcnt(0)
	s_barrier
	v_add_u32_e32 v2, s27, v169
	s_waitcnt vmcnt(4)
	s_setprio 1
	ds_read_b128 v[88:91], v2 offset:0
	ds_read_b128 v[92:95], v2 offset:64
	s_waitcnt vmcnt(3)
	ds_read_b128 v[96:99], v2 offset:0x80
	s_waitcnt vmcnt(2)
	ds_read_b128 v[100:103], v2 offset:0xc0
	s_waitcnt vmcnt(1)
	ds_read_b128 v[104:107], v2 offset:0x1200
	s_waitcnt vmcnt(0)
	ds_read_b128 v[108:111], v2 offset:0x1240
	ds_read_b128 v[128:131], v2 offset:0x1280
	ds_read_b128 v[132:135], v2 offset:0x12c0
	s_waitcnt lgkmcnt(4)
	v_mfma_f32_16x16x32_bf16 v[88:91], v[88:91], v[12:15], 0
	v_mfma_f32_16x16x32_bf16 v[88:91], v[92:95], v[16:19], v[88:91]
	v_mfma_f32_16x16x32_bf16 v[88:91], v[96:99], v[20:23], v[88:91]
	ds_read_b128 v[96:99], v2 offset:0x2400
	v_mfma_f32_16x16x32_bf16 v[88:91], v[100:103], v[8:11], v[88:91]
	ds_read_b128 v[100:103], v2 offset:0x2440
	ds_read_b128 v[136:139], v2 offset:0x2480
	ds_read_b128 v[140:143], v2 offset:0x24c0
	s_waitcnt lgkmcnt(4)
	v_mfma_f32_16x16x32_bf16 v[92:95], v[104:107], v[12:15], 0
	ds_read_b128 v[104:107], v2 offset:0x3600
	v_mfma_f32_16x16x32_bf16 v[92:95], v[108:111], v[16:19], v[92:95]
	ds_read_b128 v[108:111], v2 offset:0x3640
	v_mfma_f32_16x16x32_bf16 v[92:95], v[128:131], v[20:23], v[92:95]
	ds_read_b128 v[128:131], v2 offset:0x3680
	v_mfma_f32_16x16x32_bf16 v[92:95], v[132:135], v[8:11], v[92:95]
	ds_read_b128 v[132:135], v2 offset:0x36c0
	s_waitcnt lgkmcnt(4)
	v_mfma_f32_16x16x32_bf16 v[96:99], v[96:99], v[12:15], 0
	s_waitcnt lgkmcnt(0)
	v_mfma_f32_16x16x32_bf16 v[96:99], v[100:103], v[16:19], v[96:99]
	v_mfma_f32_16x16x32_bf16 v[96:99], v[136:139], v[20:23], v[96:99]
	v_mfma_f32_16x16x32_bf16 v[96:99], v[140:143], v[8:11], v[96:99]
	v_mfma_f32_16x16x32_bf16 v[12:15], v[104:107], v[12:15], 0
	s_andn2_b64 vcc, exec, s[44:45]
	v_mfma_f32_16x16x32_bf16 v[12:15], v[108:111], v[16:19], v[12:15]
	v_mfma_f32_16x16x32_bf16 v[12:15], v[128:131], v[20:23], v[12:15]
	v_mfma_f32_16x16x32_bf16 v[12:15], v[132:135], v[8:11], v[12:15]
	s_cbranch_vccz .LBB0_422
	v_add_u32_e32 v2, s7, v167
	v_cvt_pk_bf16_f32 v8, v112, v113
	v_cvt_pk_bf16_f32 v9, v114, v115
	v_cvt_pk_bf16_f32 v10, v116, v117
	v_cvt_pk_bf16_f32 v11, v118, v119
	v_cvt_pk_bf16_f32 v16, v120, v121
	v_cvt_pk_bf16_f32 v17, v122, v123
	v_cvt_pk_bf16_f32 v18, v124, v125
	v_cvt_pk_bf16_f32 v19, v126, v127
	ds_read_b64_tr_b16 v[20:21], v2 offset:0
	ds_read_b64_tr_b16 v[22:23], v2 offset:0x2200
	ds_read_b64_tr_b16 v[100:101], v2 offset:0x4400
	ds_read_b64_tr_b16 v[102:103], v2 offset:0x6600
	ds_read_b64_tr_b16 v[104:105], v2 offset:32
	ds_read_b64_tr_b16 v[106:107], v2 offset:0x2220
	ds_read_b64_tr_b16 v[108:109], v2 offset:0x4420
	ds_read_b64_tr_b16 v[110:111], v2 offset:0x6620
	ds_read_b64_tr_b16 v[112:113], v2 offset:64
	ds_read_b64_tr_b16 v[114:115], v2 offset:0x2240
	ds_read_b64_tr_b16 v[116:117], v2 offset:0x4440
	ds_read_b64_tr_b16 v[118:119], v2 offset:0x6640
	ds_read_b64_tr_b16 v[120:121], v2 offset:0x60
	ds_read_b64_tr_b16 v[122:123], v2 offset:0x2260
	ds_read_b64_tr_b16 v[124:125], v2 offset:0x4460
	ds_read_b64_tr_b16 v[126:127], v2 offset:0x6660
	s_waitcnt lgkmcnt(8)
	s_nop 0
	v_mfma_f32_16x16x32_bf16 v[20:23], v[8:11], v[20:23], v[84:87]
	v_mfma_f32_16x16x32_bf16 v[84:87], v[16:19], v[100:103], v[20:23]
	v_mfma_f32_16x16x32_bf16 v[20:23], v[8:11], v[104:107], v[80:83]
	v_mfma_f32_16x16x32_bf16 v[80:83], v[16:19], v[108:111], v[20:23]
	ds_read_b64_tr_b16 v[20:21], v2 offset:0x80
	ds_read_b64_tr_b16 v[22:23], v2 offset:0x2280
	ds_read_b64_tr_b16 v[100:101], v2 offset:0x4480
	ds_read_b64_tr_b16 v[102:103], v2 offset:0x6680
	ds_read_b64_tr_b16 v[104:105], v2 offset:0xa0
	ds_read_b64_tr_b16 v[106:107], v2 offset:0x22a0
	ds_read_b64_tr_b16 v[108:109], v2 offset:0x44a0
	ds_read_b64_tr_b16 v[110:111], v2 offset:0x66a0
	s_waitcnt lgkmcnt(8)
	v_mfma_f32_16x16x32_bf16 v[76:79], v[8:11], v[112:115], v[76:79]
	ds_read_b64_tr_b16 v[112:113], v2 offset:0xc0
	ds_read_b64_tr_b16 v[114:115], v2 offset:0x22c0
	v_mfma_f32_16x16x32_bf16 v[76:79], v[16:19], v[116:119], v[76:79]
	ds_read_b64_tr_b16 v[116:117], v2 offset:0x44c0
	ds_read_b64_tr_b16 v[118:119], v2 offset:0x66c0
	v_mfma_f32_16x16x32_bf16 v[72:75], v[8:11], v[120:123], v[72:75]
	ds_read_b64_tr_b16 v[120:121], v2 offset:0xe0
	ds_read_b64_tr_b16 v[122:123], v2 offset:0x22e0
	v_mfma_f32_16x16x32_bf16 v[72:75], v[16:19], v[124:127], v[72:75]
	ds_read_b64_tr_b16 v[124:125], v2 offset:0x44e0
	ds_read_b64_tr_b16 v[126:127], v2 offset:0x66e0
	s_waitcnt lgkmcnt(8)
	s_nop 2
	v_mfma_f32_16x16x32_bf16 v[20:23], v[8:11], v[20:23], v[68:71]
	v_mfma_f32_16x16x32_bf16 v[68:71], v[16:19], v[100:103], v[20:23]
	v_mfma_f32_16x16x32_bf16 v[20:23], v[8:11], v[104:107], v[64:67]
	v_mfma_f32_16x16x32_bf16 v[64:67], v[16:19], v[108:111], v[20:23]
	ds_read_b64_tr_b16 v[20:21], v2 offset:0x100
	ds_read_b64_tr_b16 v[22:23], v2 offset:0x2300
	ds_read_b64_tr_b16 v[100:101], v2 offset:0x4500
	ds_read_b64_tr_b16 v[102:103], v2 offset:0x6700
	ds_read_b64_tr_b16 v[104:105], v2 offset:0x120
	ds_read_b64_tr_b16 v[106:107], v2 offset:0x2320
	ds_read_b64_tr_b16 v[108:109], v2 offset:0x4520
	ds_read_b64_tr_b16 v[110:111], v2 offset:0x6720
	s_waitcnt lgkmcnt(8)
	v_mfma_f32_16x16x32_bf16 v[60:63], v[8:11], v[112:115], v[60:63]
	ds_read_b64_tr_b16 v[112:113], v2 offset:0x140
	ds_read_b64_tr_b16 v[114:115], v2 offset:0x2340
	v_mfma_f32_16x16x32_bf16 v[60:63], v[16:19], v[116:119], v[60:63]
	ds_read_b64_tr_b16 v[116:117], v2 offset:0x4540
	ds_read_b64_tr_b16 v[118:119], v2 offset:0x6740
	v_mfma_f32_16x16x32_bf16 v[56:59], v[8:11], v[120:123], v[56:59]
	ds_read_b64_tr_b16 v[120:121], v2 offset:0x160
	ds_read_b64_tr_b16 v[122:123], v2 offset:0x2360
	v_mfma_f32_16x16x32_bf16 v[56:59], v[16:19], v[124:127], v[56:59]
	ds_read_b64_tr_b16 v[124:125], v2 offset:0x4560
	ds_read_b64_tr_b16 v[126:127], v2 offset:0x6760
	s_waitcnt lgkmcnt(8)
	s_nop 2
	v_mfma_f32_16x16x32_bf16 v[20:23], v[8:11], v[20:23], v[48:51]
	v_mfma_f32_16x16x32_bf16 v[48:51], v[16:19], v[100:103], v[20:23]
	v_mfma_f32_16x16x32_bf16 v[20:23], v[8:11], v[104:107], v[40:43]
	v_mfma_f32_16x16x32_bf16 v[40:43], v[16:19], v[108:111], v[20:23]
	ds_read_b64_tr_b16 v[20:21], v2 offset:0x180
	ds_read_b64_tr_b16 v[22:23], v2 offset:0x2380
	ds_read_b64_tr_b16 v[100:101], v2 offset:0x4580
	ds_read_b64_tr_b16 v[102:103], v2 offset:0x6780
	ds_read_b64_tr_b16 v[104:105], v2 offset:0x1a0
	ds_read_b64_tr_b16 v[106:107], v2 offset:0x23a0
	ds_read_b64_tr_b16 v[108:109], v2 offset:0x45a0
	ds_read_b64_tr_b16 v[110:111], v2 offset:0x67a0
	s_waitcnt lgkmcnt(8)
	v_mfma_f32_16x16x32_bf16 v[36:39], v[8:11], v[112:115], v[36:39]
	ds_read_b64_tr_b16 v[112:113], v2 offset:0x1c0
	ds_read_b64_tr_b16 v[114:115], v2 offset:0x23c0
	v_mfma_f32_16x16x32_bf16 v[36:39], v[16:19], v[116:119], v[36:39]
	ds_read_b64_tr_b16 v[116:117], v2 offset:0x45c0
	ds_read_b64_tr_b16 v[118:119], v2 offset:0x67c0
	v_mfma_f32_16x16x32_bf16 v[28:31], v[8:11], v[120:123], v[28:31]
	ds_read_b64_tr_b16 v[120:121], v2 offset:0x1e0
	ds_read_b64_tr_b16 v[122:123], v2 offset:0x23e0
	v_mfma_f32_16x16x32_bf16 v[28:31], v[16:19], v[124:127], v[28:31]
	ds_read_b64_tr_b16 v[124:125], v2 offset:0x45e0
	ds_read_b64_tr_b16 v[126:127], v2 offset:0x67e0
	s_waitcnt lgkmcnt(8)
	s_nop 2
	v_mfma_f32_16x16x32_bf16 v[20:23], v[8:11], v[20:23], v[44:47]
	s_waitcnt lgkmcnt(0)
	v_mfma_f32_16x16x32_bf16 v[44:47], v[16:19], v[100:103], v[20:23]
	v_mfma_f32_16x16x32_bf16 v[20:23], v[8:11], v[104:107], v[52:55]
	v_mfma_f32_16x16x32_bf16 v[52:55], v[16:19], v[108:111], v[20:23]
	v_mfma_f32_16x16x32_bf16 v[20:23], v[8:11], v[112:115], v[32:35]
	v_mfma_f32_16x16x32_bf16 v[8:11], v[8:11], v[120:123], v[24:27]
	v_mfma_f32_16x16x32_bf16 v[32:35], v[16:19], v[116:119], v[20:23]
	v_mfma_f32_16x16x32_bf16 v[24:27], v[16:19], v[124:127], v[8:11]
	s_setprio 0
.LBB0_422:
	s_setprio 0
	s_sub_i32 s1, s13, s54
	s_lshl_b32 s1, s1, 6
	v_cvt_f32_i32_e32 v2, s1
	s_waitcnt lgkmcnt(0)
	s_barrier
	s_or_b32 s4, s1, 63
	s_mov_b64 s[2:3], -1
	v_sub_f32_e32 v108, v5, v2
	v_add_f32_e32 v106, 0xc1800000, v108
	v_add_f32_e32 v104, 0xc2000000, v108
	v_add_f32_e32 v4, 0xc2400000, v108
	s_cmp_lt_i32 s4, s96
	v_add_f32_e32 v109, -1.0, v108
	v_add_f32_e32 v107, -1.0, v106
	v_add_f32_e32 v105, -1.0, v104
	v_add_f32_e32 v5, -1.0, v4
	s_cbranch_scc1 .LBB0_426
	v_pk_add_f32 v[16:17], v[106:107], -2.0 op_sel_hi:[1,0]
	v_and_b32_e32 v20, 0x7fffffff, v106
	v_and_b32_e32 v17, 0x7fffffff, v17
	v_and_b32_e32 v16, 0x7fffffff, v16
	v_and_b32_e32 v21, 0x7fffffff, v107
	v_pk_fma_f32 v[18:19], v[16:17], v[146:147], v[94:95] op_sel_hi:[1,0,1]
	v_pk_fma_f32 v[16:17], v[20:21], v[146:147], v[92:93] op_sel_hi:[1,0,1]
	v_pk_add_f32 v[20:21], v[104:105], -2.0 op_sel_hi:[1,0]
	v_and_b32_e32 v100, 0x7fffffff, v104
	v_and_b32_e32 v21, 0x7fffffff, v21
	v_and_b32_e32 v20, 0x7fffffff, v20
	v_and_b32_e32 v101, 0x7fffffff, v105
	v_pk_add_f32 v[8:9], v[108:109], -2.0 op_sel_hi:[1,0]
	v_pk_fma_f32 v[22:23], v[20:21], v[146:147], v[98:99] op_sel_hi:[1,0,1]
	v_pk_fma_f32 v[20:21], v[100:101], v[146:147], v[96:97] op_sel_hi:[1,0,1]
	v_pk_add_f32 v[100:101], v[4:5], -2.0 op_sel_hi:[1,0]
	s_sub_i32 s1, s12, s1
	v_and_b32_e32 v11, 0x7fffffff, v9
	v_and_b32_e32 v10, 0x7fffffff, v8
	v_and_b32_e32 v8, 0x7fffffff, v108
	v_and_b32_e32 v9, 0x7fffffff, v109
	v_and_b32_e32 v101, 0x7fffffff, v101
	v_and_b32_e32 v100, 0x7fffffff, v100
	v_and_b32_e32 v110, 0x7fffffff, v4
	v_and_b32_e32 v111, 0x7fffffff, v5
	v_pk_fma_f32 v[8:9], v[8:9], v[146:147], v[88:89] op_sel_hi:[1,0,1]
	v_pk_fma_f32 v[10:11], v[10:11], v[146:147], v[90:91] op_sel_hi:[1,0,1]
	v_pk_fma_f32 v[102:103], v[100:101], v[146:147], v[14:15] op_sel_hi:[1,0,1]
	s_cmp_lt_i32 s1, 64
	v_pk_fma_f32 v[100:101], v[110:111], v[146:147], v[12:13] op_sel_hi:[1,0,1]
	s_cbranch_scc0 .LBB0_425
	v_or_b32_e32 v2, 1, v166
	v_cmp_gt_i32_e64 s[42:43], s1, v2
	v_or_b32_e32 v2, 2, v166
	v_cmp_gt_i32_e64 s[44:45], s1, v2
	v_or_b32_e32 v2, 3, v166
	v_cmp_gt_i32_e64 s[46:47], s1, v2
	s_or_b64 s[44:45], s[46:47], s[44:45]
	v_cmp_gt_i32_e32 vcc, s1, v166
	s_or_b64 s[42:43], s[44:45], s[42:43]
	s_or_b64 vcc, s[42:43], vcc
	v_or_b32_e32 v2, 16, v166
	v_cndmask_b32_e32 v8, v202, v8, vcc
	v_cmp_gt_i32_e32 vcc, s1, v2
	v_or_b32_e32 v2, 17, v166
	v_cndmask_b32_e64 v9, v202, v9, s[42:43]
	v_cmp_gt_i32_e64 s[42:43], s1, v2
	v_or_b32_e32 v2, 18, v166
	v_cndmask_b32_e64 v10, v202, v10, s[44:45]
	v_cmp_gt_i32_e64 s[44:45], s1, v2
	v_or_b32_e32 v2, 19, v166
	v_cndmask_b32_e64 v11, v202, v11, s[46:47]
	v_cmp_gt_i32_e64 s[46:47], s1, v2
	s_or_b64 s[44:45], s[46:47], s[44:45]
	s_or_b64 s[42:43], s[44:45], s[42:43]
	s_or_b64 vcc, s[42:43], vcc
	v_or_b32_e32 v2, 32, v166
	v_cndmask_b32_e32 v16, v202, v16, vcc
	v_cmp_gt_i32_e32 vcc, s1, v2
	v_or_b32_e32 v2, 33, v166
	v_cndmask_b32_e64 v17, v202, v17, s[42:43]
	v_cmp_gt_i32_e64 s[42:43], s1, v2
	v_or_b32_e32 v2, 34, v166
	v_cndmask_b32_e64 v18, v202, v18, s[44:45]
	v_cmp_gt_i32_e64 s[44:45], s1, v2
	v_or_b32_e32 v2, 35, v166
	v_cndmask_b32_e64 v19, v202, v19, s[46:47]
	v_cmp_gt_i32_e64 s[46:47], s1, v2
	s_or_b64 s[44:45], s[46:47], s[44:45]
	s_or_b64 s[42:43], s[44:45], s[42:43]
	s_or_b64 vcc, s[42:43], vcc
	v_or_b32_e32 v2, 48, v166
	v_cndmask_b32_e32 v20, v202, v20, vcc
	v_cmp_gt_i32_e32 vcc, s1, v2
	v_or_b32_e32 v2, 49, v166
	v_cndmask_b32_e64 v21, v202, v21, s[42:43]
	v_cmp_gt_i32_e64 s[42:43], s1, v2
	v_or_b32_e32 v2, 50, v166
	v_cndmask_b32_e64 v22, v202, v22, s[44:45]
	v_cmp_gt_i32_e64 s[44:45], s1, v2
	v_or_b32_e32 v2, 51, v166
	v_cndmask_b32_e64 v23, v202, v23, s[46:47]
	v_cmp_gt_i32_e64 s[46:47], s1, v2
	s_or_b64 s[44:45], s[46:47], s[44:45]
	s_or_b64 s[42:43], s[44:45], s[42:43]
	s_or_b64 vcc, s[42:43], vcc
	v_cndmask_b32_e64 v103, v202, v103, s[46:47]
	v_cndmask_b32_e64 v102, v202, v102, s[44:45]
	v_cndmask_b32_e64 v101, v202, v101, s[42:43]
	v_cndmask_b32_e32 v100, v202, v100, vcc

.LBB0_444:
	v_lshrrev_b32_e32 v5, 2, v32
	v_and_b32_e32 v216, 12, v5
	v_mul_u32_u24_e32 v5, 0x120, v33
	v_add3_u32 v220, v8, 0, v5
	s_setprio 1
	ds_read_b128 v[8:11], v220 offset:0
	ds_read_b128 v[12:15], v220 offset:64
	ds_read_b128 v[16:19], v220 offset:0x80
	ds_read_b128 v[20:23], v220 offset:0xc0
	ds_read_b128 v[24:27], v220 offset:0x1200
	s_add_i32 s26, s4, s26
	v_sub_u32_e32 v5, v33, v216
	ds_read_b128 v[28:31], v220 offset:0x1240
	v_add_u32_e32 v5, s26, v5
	ds_read_b128 v[34:37], v220 offset:0x1280
	v_cvt_f32_i32_e32 v5, v5
	ds_read_b128 v[38:41], v220 offset:0x12c0
	s_waitcnt lgkmcnt(4)
	v_mfma_f32_16x16x32_bf16 v[8:11], v[8:11], v[48:51], 0
	v_mfma_f32_16x16x32_bf16 v[8:11], v[12:15], v[52:55], v[8:11]
	v_mfma_f32_16x16x32_bf16 v[8:11], v[16:19], v[56:59], v[8:11]
	ds_read_b128 v[16:19], v220 offset:0x2400
	v_mfma_f32_16x16x32_bf16 v[8:11], v[20:23], v[84:87], v[8:11]
	ds_read_b128 v[20:23], v220 offset:0x2440
	ds_read_b128 v[42:45], v220 offset:0x2480
	ds_read_b128 v[60:63], v220 offset:0x24c0
	s_waitcnt lgkmcnt(4)
	v_mfma_f32_16x16x32_bf16 v[12:15], v[24:27], v[48:51], 0
	ds_read_b128 v[24:27], v220 offset:0x3600
	v_mfma_f32_16x16x32_bf16 v[12:15], v[28:31], v[52:55], v[12:15]
	ds_read_b128 v[28:31], v220 offset:0x3640
	v_mfma_f32_16x16x32_bf16 v[12:15], v[34:37], v[56:59], v[12:15]
	ds_read_b128 v[34:37], v220 offset:0x3680
	v_mfma_f32_16x16x32_bf16 v[12:15], v[38:41], v[84:87], v[12:15]
	ds_read_b128 v[38:41], v220 offset:0x36c0
	s_waitcnt lgkmcnt(4)
	v_mfma_f32_16x16x32_bf16 v[16:19], v[16:19], v[48:51], 0
	s_waitcnt lgkmcnt(0)
	v_mfma_f32_16x16x32_bf16 v[16:19], v[20:23], v[52:55], v[16:19]
	v_mfma_f32_16x16x32_bf16 v[16:19], v[42:45], v[56:59], v[16:19]
	v_mfma_f32_16x16x32_bf16 v[20:23], v[60:63], v[84:87], v[16:19]
	v_mfma_f32_16x16x32_bf16 v[16:19], v[24:27], v[48:51], 0
	s_waitcnt lgkmcnt(0)
	s_barrier
	s_mov_b64 s[4:5], -1
	s_cmp_lt_i32 s28, s26
	v_mfma_f32_16x16x32_bf16 v[16:19], v[28:31], v[52:55], v[16:19]
	v_sub_f32_e32 v30, v5, v213
	v_add_f32_e32 v28, 0xc1800000, v30
	v_add_f32_e32 v26, 0xc2000000, v30
	v_mfma_f32_16x16x32_bf16 v[16:19], v[34:37], v[56:59], v[16:19]
	v_add_f32_e32 v24, 0xc2400000, v30
	v_add_f32_e32 v31, -1.0, v30
	v_add_f32_e32 v29, -1.0, v28
	v_mfma_f32_16x16x32_bf16 v[16:19], v[38:41], v[84:87], v[16:19]
	s_setprio 0
	v_add_f32_e32 v27, -1.0, v26
	v_add_f32_e32 v25, -1.0, v24
	s_cbranch_scc1 .LBB0_448
	v_pk_add_f32 v[34:35], v[30:31], -2.0 op_sel_hi:[1,0]
	v_and_b32_e32 v36, 0x7fffffff, v30
	v_and_b32_e32 v35, 0x7fffffff, v35
	v_and_b32_e32 v34, 0x7fffffff, v34
	v_pk_fma_f32 v[114:115], v[34:35], v[146:147], v[10:11] op_sel_hi:[1,0,1]
	v_pk_add_f32 v[34:35], v[28:29], -2.0 op_sel_hi:[1,0]
	v_and_b32_e32 v37, 0x7fffffff, v31
	v_and_b32_e32 v35, 0x7fffffff, v35
	v_and_b32_e32 v34, 0x7fffffff, v34
	v_pk_fma_f32 v[118:119], v[34:35], v[146:147], v[14:15] op_sel_hi:[1,0,1]
	v_pk_add_f32 v[34:35], v[26:27], -2.0 op_sel_hi:[1,0]
	v_pk_fma_f32 v[112:113], v[36:37], v[146:147], v[8:9] op_sel_hi:[1,0,1]
	v_and_b32_e32 v36, 0x7fffffff, v28
	v_and_b32_e32 v37, 0x7fffffff, v29
	v_and_b32_e32 v35, 0x7fffffff, v35
	v_and_b32_e32 v34, 0x7fffffff, v34
	v_pk_fma_f32 v[116:117], v[36:37], v[146:147], v[12:13] op_sel_hi:[1,0,1]
	v_and_b32_e32 v36, 0x7fffffff, v26
	v_and_b32_e32 v37, 0x7fffffff, v27
	v_pk_fma_f32 v[122:123], v[34:35], v[146:147], v[22:23] op_sel_hi:[1,0,1]
	v_pk_add_f32 v[34:35], v[24:25], -2.0 op_sel_hi:[1,0]
	v_pk_fma_f32 v[120:121], v[36:37], v[146:147], v[20:21] op_sel_hi:[1,0,1]
	v_and_b32_e32 v35, 0x7fffffff, v35
	v_and_b32_e32 v34, 0x7fffffff, v34
	v_and_b32_e32 v36, 0x7fffffff, v24
	v_and_b32_e32 v37, 0x7fffffff, v25
	v_pk_fma_f32 v[126:127], v[34:35], v[146:147], v[18:19] op_sel_hi:[1,0,1]
	s_cmp_lt_i32 s14, 64
	v_pk_fma_f32 v[124:125], v[36:37], v[146:147], v[16:17] op_sel_hi:[1,0,1]
	s_cbranch_scc0 .LBB0_447
	v_or_b32_e32 v34, 1, v216
	v_cmp_gt_i32_e64 s[42:43], s14, v34
	v_or_b32_e32 v34, 2, v216
	v_cmp_gt_i32_e64 s[44:45], s14, v34
	v_or_b32_e32 v34, 3, v216
	v_cmp_gt_i32_e64 s[46:47], s14, v34
	s_or_b64 s[44:45], s[46:47], s[44:45]
	v_cmp_gt_i32_e32 vcc, s14, v216
	s_or_b64 s[42:43], s[44:45], s[42:43]
	s_or_b64 vcc, s[42:43], vcc
	v_or_b32_e32 v34, 16, v216
	v_cndmask_b32_e32 v112, v202, v112, vcc
	v_cmp_gt_i32_e32 vcc, s14, v34
	v_or_b32_e32 v34, 17, v216
	v_cndmask_b32_e64 v113, v202, v113, s[42:43]
	v_cmp_gt_i32_e64 s[42:43], s14, v34
	v_or_b32_e32 v34, 18, v216
	v_cndmask_b32_e64 v114, v202, v114, s[44:45]
	v_cmp_gt_i32_e64 s[44:45], s14, v34
	v_or_b32_e32 v34, 19, v216
	v_cndmask_b32_e64 v115, v202, v115, s[46:47]
	v_cmp_gt_i32_e64 s[46:47], s14, v34
	s_or_b64 s[44:45], s[46:47], s[44:45]
	s_or_b64 s[42:43], s[44:45], s[42:43]
	s_or_b64 vcc, s[42:43], vcc
	v_or_b32_e32 v34, 32, v216
	v_cndmask_b32_e32 v116, v202, v116, vcc
	v_cmp_gt_i32_e32 vcc, s14, v34
	v_or_b32_e32 v34, 33, v216
	v_cndmask_b32_e64 v117, v202, v117, s[42:43]
	v_cmp_gt_i32_e64 s[42:43], s14, v34
	v_or_b32_e32 v34, 34, v216
	v_cndmask_b32_e64 v118, v202, v118, s[44:45]
	v_cmp_gt_i32_e64 s[44:45], s14, v34
	v_or_b32_e32 v34, 35, v216
	v_cndmask_b32_e64 v119, v202, v119, s[46:47]
	v_cmp_gt_i32_e64 s[46:47], s14, v34
	s_or_b64 s[44:45], s[46:47], s[44:45]
	s_or_b64 s[42:43], s[44:45], s[42:43]
	s_or_b64 vcc, s[42:43], vcc
	v_or_b32_e32 v34, 48, v216
	v_cndmask_b32_e32 v120, v202, v120, vcc
	v_cmp_gt_i32_e32 vcc, s14, v34
	v_or_b32_e32 v34, 49, v216
	v_cndmask_b32_e64 v121, v202, v121, s[42:43]
	v_cmp_gt_i32_e64 s[42:43], s14, v34
	v_or_b32_e32 v34, 50, v216
	v_cndmask_b32_e64 v122, v202, v122, s[44:45]
	v_cmp_gt_i32_e64 s[44:45], s14, v34
	v_or_b32_e32 v34, 51, v216
	v_cndmask_b32_e64 v123, v202, v123, s[46:47]
	v_cmp_gt_i32_e64 s[46:47], s14, v34
	s_or_b64 s[44:45], s[46:47], s[44:45]
	s_or_b64 s[42:43], s[44:45], s[42:43]
	s_or_b64 vcc, s[42:43], vcc
	v_cndmask_b32_e64 v127, v202, v127, s[46:47]
	v_cndmask_b32_e64 v126, v202, v126, s[44:45]
	v_cndmask_b32_e64 v125, v202, v125, s[42:43]
	v_cndmask_b32_e32 v124, v202, v124, vcc

.LBB0_454:
	v_add_u32_e32 v2, s27, v167
	v_cvt_pk_bf16_f32 v8, v8, v9
	v_cvt_pk_bf16_f32 v9, v10, v11
	v_cvt_pk_bf16_f32 v10, v16, v17
	v_cvt_pk_bf16_f32 v11, v18, v19
	v_cvt_pk_bf16_f32 v12, v20, v21
	v_cvt_pk_bf16_f32 v13, v22, v23
	v_cvt_pk_bf16_f32 v14, v100, v101
	v_cvt_pk_bf16_f32 v15, v102, v103
	s_setprio 1
	ds_read_b64_tr_b16 v[16:17], v2 offset:0
	ds_read_b64_tr_b16 v[18:19], v2 offset:0x2200
	ds_read_b64_tr_b16 v[20:21], v2 offset:0x4400
	ds_read_b64_tr_b16 v[22:23], v2 offset:0x6600
	ds_read_b64_tr_b16 v[88:89], v2 offset:32
	ds_read_b64_tr_b16 v[90:91], v2 offset:0x2220
	ds_read_b64_tr_b16 v[92:93], v2 offset:0x4420
	ds_read_b64_tr_b16 v[94:95], v2 offset:0x6620
	ds_read_b64_tr_b16 v[96:97], v2 offset:64
	ds_read_b64_tr_b16 v[98:99], v2 offset:0x2240
	ds_read_b64_tr_b16 v[100:101], v2 offset:0x4440
	ds_read_b64_tr_b16 v[102:103], v2 offset:0x6640
	ds_read_b64_tr_b16 v[104:105], v2 offset:0x60
	ds_read_b64_tr_b16 v[106:107], v2 offset:0x2260
	ds_read_b64_tr_b16 v[108:109], v2 offset:0x4460
	ds_read_b64_tr_b16 v[110:111], v2 offset:0x6660
	s_waitcnt lgkmcnt(8)
	s_nop 0
	v_mfma_f32_16x16x32_bf16 v[16:19], v[8:11], v[16:19], v[84:87]
	v_mfma_f32_16x16x32_bf16 v[84:87], v[12:15], v[20:23], v[16:19]
	v_mfma_f32_16x16x32_bf16 v[16:19], v[8:11], v[88:91], v[80:83]
	v_mfma_f32_16x16x32_bf16 v[80:83], v[12:15], v[92:95], v[16:19]
	ds_read_b64_tr_b16 v[16:17], v2 offset:0x80
	ds_read_b64_tr_b16 v[18:19], v2 offset:0x2280
	ds_read_b64_tr_b16 v[20:21], v2 offset:0x4480
	ds_read_b64_tr_b16 v[22:23], v2 offset:0x6680
	ds_read_b64_tr_b16 v[88:89], v2 offset:0xa0
	ds_read_b64_tr_b16 v[90:91], v2 offset:0x22a0
	ds_read_b64_tr_b16 v[92:93], v2 offset:0x44a0
	ds_read_b64_tr_b16 v[94:95], v2 offset:0x66a0
	s_waitcnt lgkmcnt(8)
	v_mfma_f32_16x16x32_bf16 v[76:79], v[8:11], v[96:99], v[76:79]
	ds_read_b64_tr_b16 v[96:97], v2 offset:0xc0
	ds_read_b64_tr_b16 v[98:99], v2 offset:0x22c0
	v_mfma_f32_16x16x32_bf16 v[76:79], v[12:15], v[100:103], v[76:79]
	ds_read_b64_tr_b16 v[100:101], v2 offset:0x44c0
	ds_read_b64_tr_b16 v[102:103], v2 offset:0x66c0
	v_mfma_f32_16x16x32_bf16 v[72:75], v[8:11], v[104:107], v[72:75]
	ds_read_b64_tr_b16 v[104:105], v2 offset:0xe0
	ds_read_b64_tr_b16 v[106:107], v2 offset:0x22e0
	v_mfma_f32_16x16x32_bf16 v[72:75], v[12:15], v[108:111], v[72:75]
	ds_read_b64_tr_b16 v[108:109], v2 offset:0x44e0
	ds_read_b64_tr_b16 v[110:111], v2 offset:0x66e0
	s_waitcnt lgkmcnt(8)
	s_nop 2
	v_mfma_f32_16x16x32_bf16 v[16:19], v[8:11], v[16:19], v[68:71]
	v_mfma_f32_16x16x32_bf16 v[68:71], v[12:15], v[20:23], v[16:19]
	v_mfma_f32_16x16x32_bf16 v[16:19], v[8:11], v[88:91], v[64:67]
	v_mfma_f32_16x16x32_bf16 v[64:67], v[12:15], v[92:95], v[16:19]
	ds_read_b64_tr_b16 v[16:17], v2 offset:0x100
	ds_read_b64_tr_b16 v[18:19], v2 offset:0x2300
	ds_read_b64_tr_b16 v[20:21], v2 offset:0x4500
	ds_read_b64_tr_b16 v[22:23], v2 offset:0x6700
	ds_read_b64_tr_b16 v[88:89], v2 offset:0x120
	ds_read_b64_tr_b16 v[90:91], v2 offset:0x2320
	ds_read_b64_tr_b16 v[92:93], v2 offset:0x4520
	ds_read_b64_tr_b16 v[94:95], v2 offset:0x6720
	s_waitcnt lgkmcnt(8)
	v_mfma_f32_16x16x32_bf16 v[60:63], v[8:11], v[96:99], v[60:63]
	ds_read_b64_tr_b16 v[96:97], v2 offset:0x140
	ds_read_b64_tr_b16 v[98:99], v2 offset:0x2340
	v_mfma_f32_16x16x32_bf16 v[60:63], v[12:15], v[100:103], v[60:63]
	ds_read_b64_tr_b16 v[100:101], v2 offset:0x4540
	ds_read_b64_tr_b16 v[102:103], v2 offset:0x6740
	v_mfma_f32_16x16x32_bf16 v[56:59], v[8:11], v[104:107], v[56:59]
	ds_read_b64_tr_b16 v[104:105], v2 offset:0x160
	ds_read_b64_tr_b16 v[106:107], v2 offset:0x2360
	v_mfma_f32_16x16x32_bf16 v[56:59], v[12:15], v[108:111], v[56:59]
	ds_read_b64_tr_b16 v[108:109], v2 offset:0x4560
	ds_read_b64_tr_b16 v[110:111], v2 offset:0x6760
	s_waitcnt lgkmcnt(8)
	s_nop 2
	v_mfma_f32_16x16x32_bf16 v[16:19], v[8:11], v[16:19], v[48:51]
	v_mfma_f32_16x16x32_bf16 v[48:51], v[12:15], v[20:23], v[16:19]
	v_mfma_f32_16x16x32_bf16 v[16:19], v[8:11], v[88:91], v[40:43]
	v_mfma_f32_16x16x32_bf16 v[40:43], v[12:15], v[92:95], v[16:19]
	ds_read_b64_tr_b16 v[16:17], v2 offset:0x180
	ds_read_b64_tr_b16 v[18:19], v2 offset:0x2380
	ds_read_b64_tr_b16 v[20:21], v2 offset:0x4580
	ds_read_b64_tr_b16 v[22:23], v2 offset:0x6780
	ds_read_b64_tr_b16 v[88:89], v2 offset:0x1a0
	ds_read_b64_tr_b16 v[90:91], v2 offset:0x23a0
	ds_read_b64_tr_b16 v[92:93], v2 offset:0x45a0
	ds_read_b64_tr_b16 v[94:95], v2 offset:0x67a0
	s_waitcnt lgkmcnt(8)
	v_mfma_f32_16x16x32_bf16 v[36:39], v[8:11], v[96:99], v[36:39]
	ds_read_b64_tr_b16 v[96:97], v2 offset:0x1c0
	ds_read_b64_tr_b16 v[98:99], v2 offset:0x23c0
	v_mfma_f32_16x16x32_bf16 v[36:39], v[12:15], v[100:103], v[36:39]
	ds_read_b64_tr_b16 v[100:101], v2 offset:0x45c0
	ds_read_b64_tr_b16 v[102:103], v2 offset:0x67c0
	v_mfma_f32_16x16x32_bf16 v[28:31], v[8:11], v[104:107], v[28:31]
	ds_read_b64_tr_b16 v[104:105], v2 offset:0x1e0
	ds_read_b64_tr_b16 v[106:107], v2 offset:0x23e0
	v_mfma_f32_16x16x32_bf16 v[28:31], v[12:15], v[108:111], v[28:31]
	ds_read_b64_tr_b16 v[108:109], v2 offset:0x45e0
	ds_read_b64_tr_b16 v[110:111], v2 offset:0x67e0
	s_waitcnt lgkmcnt(8)
	s_nop 2
	v_mfma_f32_16x16x32_bf16 v[16:19], v[8:11], v[16:19], v[44:47]
	s_waitcnt lgkmcnt(0)
	v_mfma_f32_16x16x32_bf16 v[44:47], v[12:15], v[20:23], v[16:19]
	v_mfma_f32_16x16x32_bf16 v[16:19], v[8:11], v[88:91], v[52:55]
	v_mfma_f32_16x16x32_bf16 v[52:55], v[12:15], v[92:95], v[16:19]
	v_mfma_f32_16x16x32_bf16 v[16:19], v[8:11], v[96:99], v[32:35]
	v_mfma_f32_16x16x32_bf16 v[8:11], v[8:11], v[104:107], v[24:27]
	v_mfma_f32_16x16x32_bf16 v[32:35], v[12:15], v[100:103], v[16:19]
	v_mfma_f32_16x16x32_bf16 v[24:27], v[12:15], v[108:111], v[8:11]
	s_setprio 0
	v_cmp_gt_u32_e32 vcc, 16, v162
	s_and_saveexec_b64 s[2:3], vcc
	s_cbranch_execnz .LBB0_437
	s_branch .LBB0_438
.LBB0_455:
	s_setprio 0
	v_mov_b32_e32 v8, 1.0
	v_mov_b32_e32 v212, 0
	v_mov_b32_e32 v218, 0xf149f2ca
	v_cmp_gt_f32_e32 vcc, 1.0, v8
	v_cmp_gt_u32_e64 s[42:43], 16, v214
	s_cbranch_vccz .LBB0_452

.LBB0_461:
	s_mul_i32 s7, s1, 0xd000
	s_mov_b32 s59, s1
	s_add_i32 s1, s7, 0
	s_add_i32 s2, s29, 0xffffff81
	v_add_u32_e32 v128, s1, v4
	s_ashr_i32 s3, s2, 31
	s_waitcnt lgkmcnt(0)
	s_barrier
	s_waitcnt vmcnt(5)
	ds_write_b128 v128, v[92:95]
	s_waitcnt vmcnt(4)
	ds_write_b128 v128, v[88:91] offset:128
	v_add_u32_e32 v88, s1, v219
	s_lshl_b64 s[2:3], s[2:3], 12
	s_waitcnt vmcnt(3)
	ds_write_b128 v88, v[96:99] offset:18432
	s_waitcnt vmcnt(2)
	ds_write_b128 v88, v[100:103] offset:18560
	s_waitcnt vmcnt(1)
	ds_write_b128 v88, v[104:107] offset:18688
	s_waitcnt vmcnt(0)
	ds_write_b128 v88, v[108:111] offset:18816
	v_lshl_add_u64 v[88:89], v[148:149], 0, s[2:3]
	v_lshl_add_u64 v[108:109], v[150:151], 0, s[2:3]
	global_load_dwordx4 v[92:95], v[88:89], off offset:256
	s_nop 0
	global_load_dwordx4 v[88:91], v[88:89], off offset:384
	s_nop 0
	global_load_dwordx4 v[96:99], v[108:109], off
	global_load_dwordx4 v[100:103], v[108:109], off offset:128
	global_load_dwordx4 v[104:107], v[108:109], off offset:256
	s_nop 0
	global_load_dwordx4 v[108:111], v[108:109], off offset:384
	s_mul_i32 s1, s28, 0xd000
	v_add_u32_e32 v147, s1, v220
	s_setprio 1
	ds_read_b128 v[128:131], v147 offset:0
	ds_read_b128 v[132:135], v147 offset:64
	ds_read_b128 v[136:139], v147 offset:0x80
	ds_read_b128 v[140:143], v147 offset:0xc0
	ds_read_b128 v[154:157], v147 offset:0x1200
	ds_read_b128 v[158:161], v147 offset:0x1240
	ds_read_b128 v[236:239], v147 offset:0x1280
	ds_read_b128 v[240:243], v147 offset:0x12c0
	s_waitcnt lgkmcnt(4)
	s_nop 0
	v_mfma_f32_16x16x32_bf16 v[128:131], v[128:131], v[48:51], 0
	v_mfma_f32_16x16x32_bf16 v[128:131], v[132:135], v[52:55], v[128:131]
	v_mfma_f32_16x16x32_bf16 v[128:131], v[136:139], v[56:59], v[128:131]
	ds_read_b128 v[136:139], v147 offset:0x2400
	v_mfma_f32_16x16x32_bf16 v[128:131], v[140:143], v[84:87], v[128:131]
	ds_read_b128 v[140:143], v147 offset:0x2440
	ds_read_b128 v[244:247], v147 offset:0x2480
	ds_read_b128 v[248:251], v147 offset:0x24c0
	s_waitcnt lgkmcnt(4)
	v_mfma_f32_16x16x32_bf16 v[132:135], v[154:157], v[48:51], 0
	ds_read_b128 v[154:157], v147 offset:0x3600
	v_mfma_f32_16x16x32_bf16 v[132:135], v[158:161], v[52:55], v[132:135]
	ds_read_b128 v[158:161], v147 offset:0x3640
	v_mfma_f32_16x16x32_bf16 v[132:135], v[236:239], v[56:59], v[132:135]
	ds_read_b128 v[236:239], v147 offset:0x3680
	v_mfma_f32_16x16x32_bf16 v[132:135], v[240:243], v[84:87], v[132:135]
	ds_read_b128 v[240:243], v147 offset:0x36c0
	s_waitcnt lgkmcnt(4)
	v_mfma_f32_16x16x32_bf16 v[136:139], v[136:139], v[48:51], 0
	s_waitcnt lgkmcnt(0)
	v_mfma_f32_16x16x32_bf16 v[136:139], v[140:143], v[52:55], v[136:139]
	v_mfma_f32_16x16x32_bf16 v[136:139], v[244:247], v[56:59], v[136:139]
	v_mfma_f32_16x16x32_bf16 v[140:143], v[248:251], v[84:87], v[136:139]
	v_mfma_f32_16x16x32_bf16 v[136:139], v[154:157], v[48:51], 0
	s_and_b64 vcc, exec, s[44:45]
	s_mul_i32 s9, s58, 0xd000
	v_mfma_f32_16x16x32_bf16 v[136:139], v[158:161], v[52:55], v[136:139]
	v_mfma_f32_16x16x32_bf16 v[136:139], v[236:239], v[56:59], v[136:139]
	v_mfma_f32_16x16x32_bf16 v[136:139], v[240:243], v[84:87], v[136:139]
	s_cbranch_vccnz .LBB0_463
	s_mul_i32 s2, s58, 0xd000
	v_add_u32_e32 v147, s2, v217
	v_cvt_pk_bf16_f32 v112, v112, v113
	v_cvt_pk_bf16_f32 v113, v114, v115
	v_cvt_pk_bf16_f32 v114, v116, v117
	v_cvt_pk_bf16_f32 v115, v118, v119
	v_cvt_pk_bf16_f32 v116, v120, v121
	v_cvt_pk_bf16_f32 v117, v122, v123
	v_cvt_pk_bf16_f32 v118, v124, v125
	v_cvt_pk_bf16_f32 v119, v126, v127
	ds_read_b64_tr_b16 v[120:121], v147 offset:0
	ds_read_b64_tr_b16 v[122:123], v147 offset:0x2200
	ds_read_b64_tr_b16 v[124:125], v147 offset:0x4400
	ds_read_b64_tr_b16 v[126:127], v147 offset:0x6600
	ds_read_b64_tr_b16 v[154:155], v147 offset:32
	ds_read_b64_tr_b16 v[156:157], v147 offset:0x2220
	ds_read_b64_tr_b16 v[158:159], v147 offset:0x4420
	ds_read_b64_tr_b16 v[160:161], v147 offset:0x6620
	ds_read_b64_tr_b16 v[236:237], v147 offset:64
	ds_read_b64_tr_b16 v[238:239], v147 offset:0x2240
	ds_read_b64_tr_b16 v[240:241], v147 offset:0x4440
	ds_read_b64_tr_b16 v[242:243], v147 offset:0x6640
	ds_read_b64_tr_b16 v[244:245], v147 offset:0x60
	ds_read_b64_tr_b16 v[246:247], v147 offset:0x2260
	ds_read_b64_tr_b16 v[248:249], v147 offset:0x4460
	ds_read_b64_tr_b16 v[250:251], v147 offset:0x6660
	s_waitcnt lgkmcnt(8)
	s_nop 0
	v_mfma_f32_16x16x32_bf16 v[80:83], v[112:115], v[120:123], v[80:83]
	ds_read_b64_tr_b16 v[120:121], v147 offset:0x80
	ds_read_b64_tr_b16 v[122:123], v147 offset:0x2280
	v_mfma_f32_16x16x32_bf16 v[80:83], v[116:119], v[124:127], v[80:83]
	ds_read_b64_tr_b16 v[124:125], v147 offset:0x4480
	ds_read_b64_tr_b16 v[126:127], v147 offset:0x6680
	v_mfma_f32_16x16x32_bf16 v[76:79], v[112:115], v[154:157], v[76:79]
	ds_read_b64_tr_b16 v[154:155], v147 offset:0xa0
	ds_read_b64_tr_b16 v[156:157], v147 offset:0x22a0
	v_mfma_f32_16x16x32_bf16 v[76:79], v[116:119], v[158:161], v[76:79]
	ds_read_b64_tr_b16 v[158:159], v147 offset:0x44a0
	ds_read_b64_tr_b16 v[160:161], v147 offset:0x66a0
	s_waitcnt lgkmcnt(8)
	v_mfma_f32_16x16x32_bf16 v[72:75], v[112:115], v[236:239], v[72:75]
	ds_read_b64_tr_b16 v[236:237], v147 offset:0xc0
	ds_read_b64_tr_b16 v[238:239], v147 offset:0x22c0
	v_mfma_f32_16x16x32_bf16 v[72:75], v[116:119], v[240:243], v[72:75]
	ds_read_b64_tr_b16 v[240:241], v147 offset:0x44c0
	ds_read_b64_tr_b16 v[242:243], v147 offset:0x66c0
	v_mfma_f32_16x16x32_bf16 v[68:71], v[112:115], v[244:247], v[68:71]
	ds_read_b64_tr_b16 v[244:245], v147 offset:0xe0
	ds_read_b64_tr_b16 v[246:247], v147 offset:0x22e0
	v_mfma_f32_16x16x32_bf16 v[68:71], v[116:119], v[248:251], v[68:71]
	ds_read_b64_tr_b16 v[248:249], v147 offset:0x44e0
	ds_read_b64_tr_b16 v[250:251], v147 offset:0x66e0
	s_waitcnt lgkmcnt(8)
	v_mfma_f32_16x16x32_bf16 v[64:67], v[112:115], v[120:123], v[64:67]
	ds_read_b64_tr_b16 v[120:121], v147 offset:0x100
	ds_read_b64_tr_b16 v[122:123], v147 offset:0x2300
	v_mfma_f32_16x16x32_bf16 v[64:67], v[116:119], v[124:127], v[64:67]
	ds_read_b64_tr_b16 v[124:125], v147 offset:0x4500
	ds_read_b64_tr_b16 v[126:127], v147 offset:0x6700
	v_mfma_f32_16x16x32_bf16 v[60:63], v[112:115], v[154:157], v[60:63]
	ds_read_b64_tr_b16 v[154:155], v147 offset:0x120
	ds_read_b64_tr_b16 v[156:157], v147 offset:0x2320
	v_mfma_f32_16x16x32_bf16 v[60:63], v[116:119], v[158:161], v[60:63]
	ds_read_b64_tr_b16 v[158:159], v147 offset:0x4520
	ds_read_b64_tr_b16 v[160:161], v147 offset:0x6720
	s_waitcnt lgkmcnt(8)
	v_mfma_f32_16x16x32_bf16 v[44:47], v[112:115], v[236:239], v[44:47]
	ds_read_b64_tr_b16 v[236:237], v147 offset:0x140
	ds_read_b64_tr_b16 v[238:239], v147 offset:0x2340
	v_mfma_f32_16x16x32_bf16 v[44:47], v[116:119], v[240:243], v[44:47]
	ds_read_b64_tr_b16 v[240:241], v147 offset:0x4540
	ds_read_b64_tr_b16 v[242:243], v147 offset:0x6740
	v_mfma_f32_16x16x32_bf16 v[40:43], v[112:115], v[244:247], v[40:43]
	ds_read_b64_tr_b16 v[244:245], v147 offset:0x160
	ds_read_b64_tr_b16 v[246:247], v147 offset:0x2360
	v_mfma_f32_16x16x32_bf16 v[40:43], v[116:119], v[248:251], v[40:43]
	ds_read_b64_tr_b16 v[248:249], v147 offset:0x4560
	ds_read_b64_tr_b16 v[250:251], v147 offset:0x6760
	s_waitcnt lgkmcnt(8)
	v_mfma_f32_16x16x32_bf16 v[32:35], v[112:115], v[120:123], v[32:35]
	ds_read_b64_tr_b16 v[120:121], v147 offset:0x180
	ds_read_b64_tr_b16 v[122:123], v147 offset:0x2380
	v_mfma_f32_16x16x32_bf16 v[32:35], v[116:119], v[124:127], v[32:35]
	ds_read_b64_tr_b16 v[124:125], v147 offset:0x4580
	ds_read_b64_tr_b16 v[126:127], v147 offset:0x6780
	v_mfma_f32_16x16x32_bf16 v[24:27], v[112:115], v[154:157], v[24:27]
	ds_read_b64_tr_b16 v[154:155], v147 offset:0x1a0
	ds_read_b64_tr_b16 v[156:157], v147 offset:0x23a0
	v_mfma_f32_16x16x32_bf16 v[24:27], v[116:119], v[158:161], v[24:27]
	ds_read_b64_tr_b16 v[158:159], v147 offset:0x45a0
	ds_read_b64_tr_b16 v[160:161], v147 offset:0x67a0
	s_waitcnt lgkmcnt(8)
	v_mfma_f32_16x16x32_bf16 v[20:23], v[112:115], v[236:239], v[20:23]
	ds_read_b64_tr_b16 v[236:237], v147 offset:0x1c0
	ds_read_b64_tr_b16 v[238:239], v147 offset:0x23c0
	v_mfma_f32_16x16x32_bf16 v[20:23], v[116:119], v[240:243], v[20:23]
	ds_read_b64_tr_b16 v[240:241], v147 offset:0x45c0
	ds_read_b64_tr_b16 v[242:243], v147 offset:0x67c0
	v_mfma_f32_16x16x32_bf16 v[12:15], v[112:115], v[244:247], v[12:15]
	ds_read_b64_tr_b16 v[244:245], v147 offset:0x1e0
	ds_read_b64_tr_b16 v[246:247], v147 offset:0x23e0
	v_mfma_f32_16x16x32_bf16 v[12:15], v[116:119], v[248:251], v[12:15]
	ds_read_b64_tr_b16 v[248:249], v147 offset:0x45e0
	ds_read_b64_tr_b16 v[250:251], v147 offset:0x67e0
	s_waitcnt lgkmcnt(8)
	v_mfma_f32_16x16x32_bf16 v[28:31], v[112:115], v[120:123], v[28:31]
	s_waitcnt lgkmcnt(0)
	v_mfma_f32_16x16x32_bf16 v[36:39], v[112:115], v[154:157], v[36:39]
	v_mfma_f32_16x16x32_bf16 v[28:31], v[116:119], v[124:127], v[28:31]
	v_mfma_f32_16x16x32_bf16 v[36:39], v[116:119], v[158:161], v[36:39]
	v_mfma_f32_16x16x32_bf16 v[16:19], v[112:115], v[236:239], v[16:19]
	v_mfma_f32_16x16x32_bf16 v[8:11], v[112:115], v[244:247], v[8:11]
	v_mfma_f32_16x16x32_bf16 v[16:19], v[116:119], v[240:243], v[16:19]
	v_mfma_f32_16x16x32_bf16 v[8:11], v[116:119], v[248:251], v[8:11]
	s_setprio 0
.LBB0_463:
	s_setprio 0
	s_add_i32 s2, s29, 1
	v_cvt_f32_i32_e32 v112, s2
	s_waitcnt lgkmcnt(0)
	s_barrier
	s_add_i32 s4, s29, 64
	s_mov_b64 s[2:3], -1
	v_sub_f32_e32 v160, v5, v112
	v_add_f32_e32 v158, 0xc1800000, v160
	v_add_f32_e32 v156, 0xc2000000, v160
	v_add_f32_e32 v154, 0xc2400000, v160
	s_cmp_lt_i32 s4, s26
	v_add_f32_e32 v161, -1.0, v160
	v_add_f32_e32 v159, -1.0, v158
	v_add_f32_e32 v157, -1.0, v156
	v_add_f32_e32 v155, -1.0, v154
	s_cbranch_scc1 .LBB0_467
	v_pk_add_f32 v[116:117], v[158:159], -2.0 op_sel_hi:[1,0]
	v_mov_b32_e32 v147, v146
	v_and_b32_e32 v117, 0x7fffffff, v117
	v_and_b32_e32 v116, 0x7fffffff, v116
	v_and_b32_e32 v120, 0x7fffffff, v158
	v_and_b32_e32 v121, 0x7fffffff, v159
	v_pk_fma_f32 v[118:119], v[116:117], v[146:147], v[134:135]
	v_pk_fma_f32 v[116:117], v[120:121], v[152:153], v[132:133]
	v_pk_add_f32 v[120:121], v[156:157], -2.0 op_sel_hi:[1,0]
	v_and_b32_e32 v124, 0x7fffffff, v156
	v_and_b32_e32 v121, 0x7fffffff, v121
	v_and_b32_e32 v120, 0x7fffffff, v120
	v_and_b32_e32 v125, 0x7fffffff, v157
	v_pk_add_f32 v[112:113], v[160:161], -2.0 op_sel_hi:[1,0]
	v_pk_fma_f32 v[122:123], v[120:121], v[146:147], v[142:143]
	v_pk_fma_f32 v[120:121], v[124:125], v[152:153], v[140:141]
	v_pk_add_f32 v[124:125], v[154:155], -2.0 op_sel_hi:[1,0]
	s_sub_i32 s2, s54, 64
	v_and_b32_e32 v115, 0x7fffffff, v113
	v_and_b32_e32 v114, 0x7fffffff, v112
	v_and_b32_e32 v112, 0x7fffffff, v160
	v_and_b32_e32 v113, 0x7fffffff, v161
	v_and_b32_e32 v125, 0x7fffffff, v125
	v_and_b32_e32 v124, 0x7fffffff, v124
	v_and_b32_e32 v236, 0x7fffffff, v154
	v_and_b32_e32 v237, 0x7fffffff, v155
	v_pk_fma_f32 v[112:113], v[112:113], v[152:153], v[128:129]
	v_pk_fma_f32 v[114:115], v[114:115], v[146:147], v[130:131]
	v_pk_fma_f32 v[126:127], v[124:125], v[146:147], v[138:139]
	s_cmp_lt_i32 s2, 64
	v_pk_fma_f32 v[124:125], v[236:237], v[152:153], v[136:137]
	s_cbranch_scc0 .LBB0_466
	v_cmp_gt_i32_e64 s[46:47], s2, v221
	v_cmp_gt_i32_e64 s[48:49], s2, v222
	v_cmp_gt_i32_e64 s[44:45], s2, v2
	s_or_b64 s[46:47], s[48:49], s[46:47]
	v_cmp_gt_i32_e32 vcc, s2, v216
	v_cndmask_b32_e64 v115, v202, v115, s[48:49]
	v_cndmask_b32_e64 v114, v202, v114, s[46:47]
	s_or_b64 s[44:45], s[46:47], s[44:45]
	v_cmp_gt_i32_e64 s[46:47], s2, v225
	v_cmp_gt_i32_e64 s[48:49], s2, v226
	v_cndmask_b32_e64 v113, v202, v113, s[44:45]
	s_or_b64 vcc, s[44:45], vcc
	v_cmp_gt_i32_e64 s[44:45], s2, v224
	s_or_b64 s[46:47], s[48:49], s[46:47]
	v_cndmask_b32_e32 v112, v202, v112, vcc
	v_cmp_gt_i32_e32 vcc, s2, v223
	v_cndmask_b32_e64 v119, v202, v119, s[48:49]
	v_cndmask_b32_e64 v118, v202, v118, s[46:47]
	s_or_b64 s[44:45], s[46:47], s[44:45]
	v_cmp_gt_i32_e64 s[46:47], s2, v229
	v_cmp_gt_i32_e64 s[48:49], s2, v230
	v_cndmask_b32_e64 v117, v202, v117, s[44:45]
	s_or_b64 vcc, s[44:45], vcc
	v_cmp_gt_i32_e64 s[44:45], s2, v228
	s_or_b64 s[46:47], s[48:49], s[46:47]
	v_cndmask_b32_e32 v116, v202, v116, vcc
	v_cmp_gt_i32_e32 vcc, s2, v227
	v_cndmask_b32_e64 v123, v202, v123, s[48:49]
	v_cndmask_b32_e64 v122, v202, v122, s[46:47]
	s_or_b64 s[44:45], s[46:47], s[44:45]
	v_cmp_gt_i32_e64 s[46:47], s2, v233
	v_cmp_gt_i32_e64 s[48:49], s2, v234
	v_cndmask_b32_e64 v121, v202, v121, s[44:45]
	s_or_b64 vcc, s[44:45], vcc
	v_cmp_gt_i32_e64 s[44:45], s2, v232
	s_or_b64 s[46:47], s[48:49], s[46:47]
	v_cndmask_b32_e32 v120, v202, v120, vcc
	v_cmp_gt_i32_e32 vcc, s2, v231
	s_or_b64 s[44:45], s[46:47], s[44:45]
	s_or_b64 vcc, s[44:45], vcc
	v_cndmask_b32_e64 v127, v202, v127, s[48:49]
	v_cndmask_b32_e64 v126, v202, v126, s[46:47]
	v_cndmask_b32_e64 v125, v202, v125, s[44:45]
	v_cndmask_b32_e32 v124, v202, v124, vcc

.LBB0_477:
	v_add_u32_e32 v147, s7, v220
	s_setprio 1
	ds_read_b128 v[128:131], v147 offset:0
	ds_read_b128 v[132:135], v147 offset:64
	ds_read_b128 v[136:139], v147 offset:0x80
	ds_read_b128 v[140:143], v147 offset:0xc0
	ds_read_b128 v[154:157], v147 offset:0x1200
	ds_read_b128 v[158:161], v147 offset:0x1240
	ds_read_b128 v[236:239], v147 offset:0x1280
	ds_read_b128 v[240:243], v147 offset:0x12c0
	s_waitcnt lgkmcnt(4)
	s_nop 0
	v_mfma_f32_16x16x32_bf16 v[128:131], v[128:131], v[48:51], 0
	v_mfma_f32_16x16x32_bf16 v[128:131], v[132:135], v[52:55], v[128:131]
	v_mfma_f32_16x16x32_bf16 v[128:131], v[136:139], v[56:59], v[128:131]
	ds_read_b128 v[136:139], v147 offset:0x2400
	v_mfma_f32_16x16x32_bf16 v[128:131], v[140:143], v[84:87], v[128:131]
	ds_read_b128 v[140:143], v147 offset:0x2440
	ds_read_b128 v[244:247], v147 offset:0x2480
	ds_read_b128 v[248:251], v147 offset:0x24c0
	s_waitcnt lgkmcnt(4)
	v_mfma_f32_16x16x32_bf16 v[132:135], v[154:157], v[48:51], 0
	ds_read_b128 v[154:157], v147 offset:0x3600
	v_mfma_f32_16x16x32_bf16 v[132:135], v[158:161], v[52:55], v[132:135]
	ds_read_b128 v[158:161], v147 offset:0x3640
	v_mfma_f32_16x16x32_bf16 v[132:135], v[236:239], v[56:59], v[132:135]
	ds_read_b128 v[236:239], v147 offset:0x3680
	v_mfma_f32_16x16x32_bf16 v[132:135], v[240:243], v[84:87], v[132:135]
	ds_read_b128 v[240:243], v147 offset:0x36c0
	s_waitcnt lgkmcnt(4)
	v_mfma_f32_16x16x32_bf16 v[136:139], v[136:139], v[48:51], 0
	s_waitcnt lgkmcnt(0)
	v_mfma_f32_16x16x32_bf16 v[136:139], v[140:143], v[52:55], v[136:139]
	v_mfma_f32_16x16x32_bf16 v[136:139], v[244:247], v[56:59], v[136:139]
	v_mfma_f32_16x16x32_bf16 v[140:143], v[248:251], v[84:87], v[136:139]
	v_mfma_f32_16x16x32_bf16 v[136:139], v[154:157], v[48:51], 0
	s_andn2_b64 vcc, exec, s[4:5]
	v_mfma_f32_16x16x32_bf16 v[136:139], v[158:161], v[52:55], v[136:139]
	v_mfma_f32_16x16x32_bf16 v[136:139], v[236:239], v[56:59], v[136:139]
	v_mfma_f32_16x16x32_bf16 v[136:139], v[240:243], v[84:87], v[136:139]
	s_cbranch_vccnz .LBB0_479
	v_add_u32_e32 v147, s1, v217
	v_cvt_pk_bf16_f32 v112, v112, v113
	v_cvt_pk_bf16_f32 v113, v114, v115
	v_cvt_pk_bf16_f32 v114, v116, v117
	v_cvt_pk_bf16_f32 v115, v118, v119
	v_cvt_pk_bf16_f32 v116, v120, v121
	v_cvt_pk_bf16_f32 v117, v122, v123
	v_cvt_pk_bf16_f32 v118, v124, v125
	v_cvt_pk_bf16_f32 v119, v126, v127
	ds_read_b64_tr_b16 v[120:121], v147 offset:0
	ds_read_b64_tr_b16 v[122:123], v147 offset:0x2200
	ds_read_b64_tr_b16 v[124:125], v147 offset:0x4400
	ds_read_b64_tr_b16 v[126:127], v147 offset:0x6600
	ds_read_b64_tr_b16 v[154:155], v147 offset:32
	ds_read_b64_tr_b16 v[156:157], v147 offset:0x2220
	ds_read_b64_tr_b16 v[158:159], v147 offset:0x4420
	ds_read_b64_tr_b16 v[160:161], v147 offset:0x6620
	ds_read_b64_tr_b16 v[236:237], v147 offset:64
	ds_read_b64_tr_b16 v[238:239], v147 offset:0x2240
	ds_read_b64_tr_b16 v[240:241], v147 offset:0x4440
	ds_read_b64_tr_b16 v[242:243], v147 offset:0x6640
	ds_read_b64_tr_b16 v[244:245], v147 offset:0x60
	ds_read_b64_tr_b16 v[246:247], v147 offset:0x2260
	ds_read_b64_tr_b16 v[248:249], v147 offset:0x4460
	ds_read_b64_tr_b16 v[250:251], v147 offset:0x6660
	s_waitcnt lgkmcnt(8)
	s_nop 0
	v_mfma_f32_16x16x32_bf16 v[80:83], v[112:115], v[120:123], v[80:83]
	ds_read_b64_tr_b16 v[120:121], v147 offset:0x80
	ds_read_b64_tr_b16 v[122:123], v147 offset:0x2280
	v_mfma_f32_16x16x32_bf16 v[80:83], v[116:119], v[124:127], v[80:83]
	ds_read_b64_tr_b16 v[124:125], v147 offset:0x4480
	ds_read_b64_tr_b16 v[126:127], v147 offset:0x6680
	v_mfma_f32_16x16x32_bf16 v[76:79], v[112:115], v[154:157], v[76:79]
	ds_read_b64_tr_b16 v[154:155], v147 offset:0xa0
	ds_read_b64_tr_b16 v[156:157], v147 offset:0x22a0
	v_mfma_f32_16x16x32_bf16 v[76:79], v[116:119], v[158:161], v[76:79]
	ds_read_b64_tr_b16 v[158:159], v147 offset:0x44a0
	ds_read_b64_tr_b16 v[160:161], v147 offset:0x66a0
	s_waitcnt lgkmcnt(8)
	v_mfma_f32_16x16x32_bf16 v[72:75], v[112:115], v[236:239], v[72:75]
	ds_read_b64_tr_b16 v[236:237], v147 offset:0xc0
	ds_read_b64_tr_b16 v[238:239], v147 offset:0x22c0
	v_mfma_f32_16x16x32_bf16 v[72:75], v[116:119], v[240:243], v[72:75]
	ds_read_b64_tr_b16 v[240:241], v147 offset:0x44c0
	ds_read_b64_tr_b16 v[242:243], v147 offset:0x66c0
	v_mfma_f32_16x16x32_bf16 v[68:71], v[112:115], v[244:247], v[68:71]
	ds_read_b64_tr_b16 v[244:245], v147 offset:0xe0
	ds_read_b64_tr_b16 v[246:247], v147 offset:0x22e0
	v_mfma_f32_16x16x32_bf16 v[68:71], v[116:119], v[248:251], v[68:71]
	ds_read_b64_tr_b16 v[248:249], v147 offset:0x44e0
	ds_read_b64_tr_b16 v[250:251], v147 offset:0x66e0
	s_waitcnt lgkmcnt(8)
	v_mfma_f32_16x16x32_bf16 v[64:67], v[112:115], v[120:123], v[64:67]
	ds_read_b64_tr_b16 v[120:121], v147 offset:0x100
	ds_read_b64_tr_b16 v[122:123], v147 offset:0x2300
	v_mfma_f32_16x16x32_bf16 v[64:67], v[116:119], v[124:127], v[64:67]
	ds_read_b64_tr_b16 v[124:125], v147 offset:0x4500
	ds_read_b64_tr_b16 v[126:127], v147 offset:0x6700
	v_mfma_f32_16x16x32_bf16 v[60:63], v[112:115], v[154:157], v[60:63]
	ds_read_b64_tr_b16 v[154:155], v147 offset:0x120
	ds_read_b64_tr_b16 v[156:157], v147 offset:0x2320
	v_mfma_f32_16x16x32_bf16 v[60:63], v[116:119], v[158:161], v[60:63]
	ds_read_b64_tr_b16 v[158:159], v147 offset:0x4520
	ds_read_b64_tr_b16 v[160:161], v147 offset:0x6720
	s_waitcnt lgkmcnt(8)
	v_mfma_f32_16x16x32_bf16 v[44:47], v[112:115], v[236:239], v[44:47]
	ds_read_b64_tr_b16 v[236:237], v147 offset:0x140
	ds_read_b64_tr_b16 v[238:239], v147 offset:0x2340
	v_mfma_f32_16x16x32_bf16 v[44:47], v[116:119], v[240:243], v[44:47]
	ds_read_b64_tr_b16 v[240:241], v147 offset:0x4540
	ds_read_b64_tr_b16 v[242:243], v147 offset:0x6740
	v_mfma_f32_16x16x32_bf16 v[40:43], v[112:115], v[244:247], v[40:43]
	ds_read_b64_tr_b16 v[244:245], v147 offset:0x160
	ds_read_b64_tr_b16 v[246:247], v147 offset:0x2360
	v_mfma_f32_16x16x32_bf16 v[40:43], v[116:119], v[248:251], v[40:43]
	ds_read_b64_tr_b16 v[248:249], v147 offset:0x4560
	ds_read_b64_tr_b16 v[250:251], v147 offset:0x6760
	s_waitcnt lgkmcnt(8)
	v_mfma_f32_16x16x32_bf16 v[32:35], v[112:115], v[120:123], v[32:35]
	ds_read_b64_tr_b16 v[120:121], v147 offset:0x180
	ds_read_b64_tr_b16 v[122:123], v147 offset:0x2380
	v_mfma_f32_16x16x32_bf16 v[32:35], v[116:119], v[124:127], v[32:35]
	ds_read_b64_tr_b16 v[124:125], v147 offset:0x4580
	ds_read_b64_tr_b16 v[126:127], v147 offset:0x6780
	v_mfma_f32_16x16x32_bf16 v[24:27], v[112:115], v[154:157], v[24:27]
	ds_read_b64_tr_b16 v[154:155], v147 offset:0x1a0
	ds_read_b64_tr_b16 v[156:157], v147 offset:0x23a0
	v_mfma_f32_16x16x32_bf16 v[24:27], v[116:119], v[158:161], v[24:27]
	ds_read_b64_tr_b16 v[158:159], v147 offset:0x45a0
	ds_read_b64_tr_b16 v[160:161], v147 offset:0x67a0
	s_waitcnt lgkmcnt(8)
	v_mfma_f32_16x16x32_bf16 v[20:23], v[112:115], v[236:239], v[20:23]
	ds_read_b64_tr_b16 v[236:237], v147 offset:0x1c0
	ds_read_b64_tr_b16 v[238:239], v147 offset:0x23c0
	v_mfma_f32_16x16x32_bf16 v[20:23], v[116:119], v[240:243], v[20:23]
	ds_read_b64_tr_b16 v[240:241], v147 offset:0x45c0
	ds_read_b64_tr_b16 v[242:243], v147 offset:0x67c0
	v_mfma_f32_16x16x32_bf16 v[12:15], v[112:115], v[244:247], v[12:15]
	ds_read_b64_tr_b16 v[244:245], v147 offset:0x1e0
	ds_read_b64_tr_b16 v[246:247], v147 offset:0x23e0
	v_mfma_f32_16x16x32_bf16 v[12:15], v[116:119], v[248:251], v[12:15]
	ds_read_b64_tr_b16 v[248:249], v147 offset:0x45e0
	ds_read_b64_tr_b16 v[250:251], v147 offset:0x67e0
	s_waitcnt lgkmcnt(8)
	v_mfma_f32_16x16x32_bf16 v[28:31], v[112:115], v[120:123], v[28:31]
	s_waitcnt lgkmcnt(0)
	v_mfma_f32_16x16x32_bf16 v[36:39], v[112:115], v[154:157], v[36:39]
	v_mfma_f32_16x16x32_bf16 v[28:31], v[116:119], v[124:127], v[28:31]
	v_mfma_f32_16x16x32_bf16 v[36:39], v[116:119], v[158:161], v[36:39]
	v_mfma_f32_16x16x32_bf16 v[16:19], v[112:115], v[236:239], v[16:19]
	v_mfma_f32_16x16x32_bf16 v[8:11], v[112:115], v[244:247], v[8:11]
	v_mfma_f32_16x16x32_bf16 v[16:19], v[116:119], v[240:243], v[16:19]
	v_mfma_f32_16x16x32_bf16 v[8:11], v[116:119], v[248:251], v[8:11]
	s_setprio 0
.LBB0_479:
	s_setprio 0
	s_sub_i32 s1, s29, 63
	v_cvt_f32_i32_e32 v112, s1
	s_waitcnt lgkmcnt(0)
	s_barrier
	s_mov_b64 s[4:5], -1
	s_cmp_lt_i32 s29, s26
	v_sub_f32_e32 v160, v5, v112
	v_add_f32_e32 v158, 0xc1800000, v160
	v_add_f32_e32 v156, 0xc2000000, v160
	v_add_f32_e32 v154, 0xc2400000, v160
	v_add_f32_e32 v161, -1.0, v160
	v_add_f32_e32 v159, -1.0, v158
	v_add_f32_e32 v157, -1.0, v156
	v_add_f32_e32 v155, -1.0, v154
	s_cbranch_scc1 .LBB0_483
	v_pk_add_f32 v[116:117], v[158:159], -2.0 op_sel_hi:[1,0]
	v_mov_b32_e32 v147, v146
	v_and_b32_e32 v117, 0x7fffffff, v117
	v_and_b32_e32 v116, 0x7fffffff, v116
	v_and_b32_e32 v120, 0x7fffffff, v158
	v_and_b32_e32 v121, 0x7fffffff, v159
	v_pk_fma_f32 v[118:119], v[116:117], v[146:147], v[134:135]
	v_pk_fma_f32 v[116:117], v[120:121], v[152:153], v[132:133]
	v_pk_add_f32 v[120:121], v[156:157], -2.0 op_sel_hi:[1,0]
	v_and_b32_e32 v124, 0x7fffffff, v156
	v_and_b32_e32 v121, 0x7fffffff, v121
	v_and_b32_e32 v120, 0x7fffffff, v120
	v_and_b32_e32 v125, 0x7fffffff, v157
	v_pk_add_f32 v[112:113], v[160:161], -2.0 op_sel_hi:[1,0]
	v_pk_fma_f32 v[122:123], v[120:121], v[146:147], v[142:143]
	v_pk_fma_f32 v[120:121], v[124:125], v[152:153], v[140:141]
	v_pk_add_f32 v[124:125], v[154:155], -2.0 op_sel_hi:[1,0]
	v_and_b32_e32 v115, 0x7fffffff, v113
	v_and_b32_e32 v114, 0x7fffffff, v112
	v_and_b32_e32 v112, 0x7fffffff, v160
	v_and_b32_e32 v113, 0x7fffffff, v161
	v_and_b32_e32 v125, 0x7fffffff, v125
	v_and_b32_e32 v124, 0x7fffffff, v124
	v_and_b32_e32 v236, 0x7fffffff, v154
	v_and_b32_e32 v237, 0x7fffffff, v155
	v_pk_fma_f32 v[112:113], v[112:113], v[152:153], v[128:129]
	v_pk_fma_f32 v[114:115], v[114:115], v[146:147], v[130:131]
	v_pk_fma_f32 v[126:127], v[124:125], v[146:147], v[138:139]
	s_cmp_lt_i32 s54, 64
	v_pk_fma_f32 v[124:125], v[236:237], v[152:153], v[136:137]
	s_cbranch_scc0 .LBB0_482
	v_cmp_gt_i32_e64 s[46:47], s54, v221
	v_cmp_gt_i32_e64 s[48:49], s54, v222
	v_cmp_gt_i32_e64 s[44:45], s54, v2
	s_or_b64 s[46:47], s[48:49], s[46:47]
	v_cmp_gt_i32_e32 vcc, s54, v216
	v_cndmask_b32_e64 v115, v202, v115, s[48:49]
	v_cndmask_b32_e64 v114, v202, v114, s[46:47]
	s_or_b64 s[44:45], s[46:47], s[44:45]
	v_cmp_gt_i32_e64 s[46:47], s54, v225
	v_cmp_gt_i32_e64 s[48:49], s54, v226
	v_cndmask_b32_e64 v113, v202, v113, s[44:45]
	s_or_b64 vcc, s[44:45], vcc
	v_cmp_gt_i32_e64 s[44:45], s54, v224
	s_or_b64 s[46:47], s[48:49], s[46:47]
	v_cndmask_b32_e32 v112, v202, v112, vcc
	v_cmp_gt_i32_e32 vcc, s54, v223
	v_cndmask_b32_e64 v119, v202, v119, s[48:49]
	v_cndmask_b32_e64 v118, v202, v118, s[46:47]
	s_or_b64 s[44:45], s[46:47], s[44:45]
	v_cmp_gt_i32_e64 s[46:47], s54, v229
	v_cmp_gt_i32_e64 s[48:49], s54, v230
	v_cndmask_b32_e64 v117, v202, v117, s[44:45]
	s_or_b64 vcc, s[44:45], vcc
	v_cmp_gt_i32_e64 s[44:45], s54, v228
	s_or_b64 s[46:47], s[48:49], s[46:47]
	v_cndmask_b32_e32 v116, v202, v116, vcc
	v_cmp_gt_i32_e32 vcc, s54, v227
	v_cndmask_b32_e64 v123, v202, v123, s[48:49]
	v_cndmask_b32_e64 v122, v202, v122, s[46:47]
	s_or_b64 s[44:45], s[46:47], s[44:45]
	v_cmp_gt_i32_e64 s[46:47], s54, v233
	v_cmp_gt_i32_e64 s[48:49], s54, v234
	v_cndmask_b32_e64 v121, v202, v121, s[44:45]
	s_or_b64 vcc, s[44:45], vcc
	v_cmp_gt_i32_e64 s[44:45], s54, v232
	s_or_b64 s[46:47], s[48:49], s[46:47]
	v_cndmask_b32_e32 v120, v202, v120, vcc
	v_cmp_gt_i32_e32 vcc, s54, v231
	s_or_b64 s[44:45], s[46:47], s[44:45]
	s_or_b64 vcc, s[44:45], vcc
	v_cndmask_b32_e64 v127, v202, v127, s[48:49]
	v_cndmask_b32_e64 v126, v202, v126, s[46:47]
	v_cndmask_b32_e64 v125, v202, v125, s[44:45]
	v_cndmask_b32_e32 v124, v202, v124, vcc

.LBB0_494:
	s_waitcnt lgkmcnt(0)
	s_barrier
	v_add_u32_e32 v2, s9, v220
	s_waitcnt vmcnt(4)
	s_setprio 1
	ds_read_b128 v[88:91], v2 offset:0
	ds_read_b128 v[92:95], v2 offset:64
	s_waitcnt vmcnt(3)
	ds_read_b128 v[96:99], v2 offset:0x80
	s_waitcnt vmcnt(2)
	ds_read_b128 v[100:103], v2 offset:0xc0
	s_waitcnt vmcnt(1)
	ds_read_b128 v[104:107], v2 offset:0x1200
	s_waitcnt vmcnt(0)
	ds_read_b128 v[108:111], v2 offset:0x1240
	ds_read_b128 v[128:131], v2 offset:0x1280
	ds_read_b128 v[132:135], v2 offset:0x12c0
	s_waitcnt lgkmcnt(4)
	v_mfma_f32_16x16x32_bf16 v[88:91], v[88:91], v[48:51], 0
	v_mfma_f32_16x16x32_bf16 v[88:91], v[92:95], v[52:55], v[88:91]
	v_mfma_f32_16x16x32_bf16 v[88:91], v[96:99], v[56:59], v[88:91]
	ds_read_b128 v[96:99], v2 offset:0x2400
	v_mfma_f32_16x16x32_bf16 v[88:91], v[100:103], v[84:87], v[88:91]
	ds_read_b128 v[100:103], v2 offset:0x2440
	ds_read_b128 v[136:139], v2 offset:0x2480
	ds_read_b128 v[140:143], v2 offset:0x24c0
	s_waitcnt lgkmcnt(4)
	v_mfma_f32_16x16x32_bf16 v[92:95], v[104:107], v[48:51], 0
	ds_read_b128 v[104:107], v2 offset:0x3600
	v_mfma_f32_16x16x32_bf16 v[92:95], v[108:111], v[52:55], v[92:95]
	ds_read_b128 v[108:111], v2 offset:0x3640
	v_mfma_f32_16x16x32_bf16 v[92:95], v[128:131], v[56:59], v[92:95]
	ds_read_b128 v[128:131], v2 offset:0x3680
	v_mfma_f32_16x16x32_bf16 v[92:95], v[132:135], v[84:87], v[92:95]
	ds_read_b128 v[132:135], v2 offset:0x36c0
	s_waitcnt lgkmcnt(4)
	v_mfma_f32_16x16x32_bf16 v[96:99], v[96:99], v[48:51], 0
	s_waitcnt lgkmcnt(0)
	v_mfma_f32_16x16x32_bf16 v[96:99], v[100:103], v[52:55], v[96:99]
	v_mfma_f32_16x16x32_bf16 v[96:99], v[136:139], v[56:59], v[96:99]
	v_mfma_f32_16x16x32_bf16 v[96:99], v[140:143], v[84:87], v[96:99]
	v_mfma_f32_16x16x32_bf16 v[48:51], v[104:107], v[48:51], 0
	s_andn2_b64 vcc, exec, s[44:45]
	v_mfma_f32_16x16x32_bf16 v[48:51], v[108:111], v[52:55], v[48:51]
	v_mfma_f32_16x16x32_bf16 v[48:51], v[128:131], v[56:59], v[48:51]
	v_mfma_f32_16x16x32_bf16 v[52:55], v[132:135], v[84:87], v[48:51]
	s_cbranch_vccz .LBB0_496
	v_add_u32_e32 v2, s7, v217
	v_cvt_pk_bf16_f32 v48, v112, v113
	v_cvt_pk_bf16_f32 v49, v114, v115
	v_cvt_pk_bf16_f32 v50, v116, v117
	v_cvt_pk_bf16_f32 v51, v118, v119
	v_cvt_pk_bf16_f32 v56, v120, v121
	v_cvt_pk_bf16_f32 v57, v122, v123
	v_cvt_pk_bf16_f32 v58, v124, v125
	v_cvt_pk_bf16_f32 v59, v126, v127
	ds_read_b64_tr_b16 v[84:85], v2 offset:0
	ds_read_b64_tr_b16 v[86:87], v2 offset:0x2200
	ds_read_b64_tr_b16 v[100:101], v2 offset:0x4400
	ds_read_b64_tr_b16 v[102:103], v2 offset:0x6600
	ds_read_b64_tr_b16 v[104:105], v2 offset:32
	ds_read_b64_tr_b16 v[106:107], v2 offset:0x2220
	ds_read_b64_tr_b16 v[108:109], v2 offset:0x4420
	ds_read_b64_tr_b16 v[110:111], v2 offset:0x6620
	ds_read_b64_tr_b16 v[112:113], v2 offset:64
	ds_read_b64_tr_b16 v[114:115], v2 offset:0x2240
	ds_read_b64_tr_b16 v[116:117], v2 offset:0x4440
	ds_read_b64_tr_b16 v[118:119], v2 offset:0x6640
	ds_read_b64_tr_b16 v[120:121], v2 offset:0x60
	ds_read_b64_tr_b16 v[122:123], v2 offset:0x2260
	ds_read_b64_tr_b16 v[124:125], v2 offset:0x4460
	ds_read_b64_tr_b16 v[126:127], v2 offset:0x6660
	s_waitcnt lgkmcnt(8)
	s_nop 4
	v_mfma_f32_16x16x32_bf16 v[80:83], v[48:51], v[84:87], v[80:83]
	ds_read_b64_tr_b16 v[84:85], v2 offset:0x80
	ds_read_b64_tr_b16 v[86:87], v2 offset:0x2280
	v_mfma_f32_16x16x32_bf16 v[80:83], v[56:59], v[100:103], v[80:83]
	ds_read_b64_tr_b16 v[100:101], v2 offset:0x4480
	ds_read_b64_tr_b16 v[102:103], v2 offset:0x6680
	v_mfma_f32_16x16x32_bf16 v[76:79], v[48:51], v[104:107], v[76:79]
	ds_read_b64_tr_b16 v[104:105], v2 offset:0xa0
	ds_read_b64_tr_b16 v[106:107], v2 offset:0x22a0
	v_mfma_f32_16x16x32_bf16 v[76:79], v[56:59], v[108:111], v[76:79]
	ds_read_b64_tr_b16 v[108:109], v2 offset:0x44a0
	ds_read_b64_tr_b16 v[110:111], v2 offset:0x66a0
	s_waitcnt lgkmcnt(8)
	v_mfma_f32_16x16x32_bf16 v[72:75], v[48:51], v[112:115], v[72:75]
	ds_read_b64_tr_b16 v[112:113], v2 offset:0xc0
	ds_read_b64_tr_b16 v[114:115], v2 offset:0x22c0
	v_mfma_f32_16x16x32_bf16 v[72:75], v[56:59], v[116:119], v[72:75]
	ds_read_b64_tr_b16 v[116:117], v2 offset:0x44c0
	ds_read_b64_tr_b16 v[118:119], v2 offset:0x66c0
	v_mfma_f32_16x16x32_bf16 v[68:71], v[48:51], v[120:123], v[68:71]
	ds_read_b64_tr_b16 v[120:121], v2 offset:0xe0
	ds_read_b64_tr_b16 v[122:123], v2 offset:0x22e0
	v_mfma_f32_16x16x32_bf16 v[68:71], v[56:59], v[124:127], v[68:71]
	ds_read_b64_tr_b16 v[124:125], v2 offset:0x44e0
	ds_read_b64_tr_b16 v[126:127], v2 offset:0x66e0
	s_waitcnt lgkmcnt(8)
	v_mfma_f32_16x16x32_bf16 v[64:67], v[48:51], v[84:87], v[64:67]
	ds_read_b64_tr_b16 v[84:85], v2 offset:0x100
	ds_read_b64_tr_b16 v[86:87], v2 offset:0x2300
	v_mfma_f32_16x16x32_bf16 v[64:67], v[56:59], v[100:103], v[64:67]
	ds_read_b64_tr_b16 v[100:101], v2 offset:0x4500
	ds_read_b64_tr_b16 v[102:103], v2 offset:0x6700
	v_mfma_f32_16x16x32_bf16 v[60:63], v[48:51], v[104:107], v[60:63]
	ds_read_b64_tr_b16 v[104:105], v2 offset:0x120
	ds_read_b64_tr_b16 v[106:107], v2 offset:0x2320
	v_mfma_f32_16x16x32_bf16 v[60:63], v[56:59], v[108:111], v[60:63]
	ds_read_b64_tr_b16 v[108:109], v2 offset:0x4520
	ds_read_b64_tr_b16 v[110:111], v2 offset:0x6720
	s_waitcnt lgkmcnt(8)
	v_mfma_f32_16x16x32_bf16 v[44:47], v[48:51], v[112:115], v[44:47]
	ds_read_b64_tr_b16 v[112:113], v2 offset:0x140
	ds_read_b64_tr_b16 v[114:115], v2 offset:0x2340
	v_mfma_f32_16x16x32_bf16 v[44:47], v[56:59], v[116:119], v[44:47]
	ds_read_b64_tr_b16 v[116:117], v2 offset:0x4540
	ds_read_b64_tr_b16 v[118:119], v2 offset:0x6740
	v_mfma_f32_16x16x32_bf16 v[40:43], v[48:51], v[120:123], v[40:43]
	ds_read_b64_tr_b16 v[120:121], v2 offset:0x160
	ds_read_b64_tr_b16 v[122:123], v2 offset:0x2360
	v_mfma_f32_16x16x32_bf16 v[40:43], v[56:59], v[124:127], v[40:43]
	ds_read_b64_tr_b16 v[124:125], v2 offset:0x4560
	ds_read_b64_tr_b16 v[126:127], v2 offset:0x6760
	s_waitcnt lgkmcnt(8)
	v_mfma_f32_16x16x32_bf16 v[32:35], v[48:51], v[84:87], v[32:35]
	ds_read_b64_tr_b16 v[84:85], v2 offset:0x180
	ds_read_b64_tr_b16 v[86:87], v2 offset:0x2380
	v_mfma_f32_16x16x32_bf16 v[32:35], v[56:59], v[100:103], v[32:35]
	ds_read_b64_tr_b16 v[100:101], v2 offset:0x4580
	ds_read_b64_tr_b16 v[102:103], v2 offset:0x6780
	v_mfma_f32_16x16x32_bf16 v[24:27], v[48:51], v[104:107], v[24:27]
	ds_read_b64_tr_b16 v[104:105], v2 offset:0x1a0
	ds_read_b64_tr_b16 v[106:107], v2 offset:0x23a0
	v_mfma_f32_16x16x32_bf16 v[24:27], v[56:59], v[108:111], v[24:27]
	ds_read_b64_tr_b16 v[108:109], v2 offset:0x45a0
	ds_read_b64_tr_b16 v[110:111], v2 offset:0x67a0
	s_waitcnt lgkmcnt(8)
	v_mfma_f32_16x16x32_bf16 v[20:23], v[48:51], v[112:115], v[20:23]
	ds_read_b64_tr_b16 v[112:113], v2 offset:0x1c0
	ds_read_b64_tr_b16 v[114:115], v2 offset:0x23c0
	v_mfma_f32_16x16x32_bf16 v[20:23], v[56:59], v[116:119], v[20:23]
	ds_read_b64_tr_b16 v[116:117], v2 offset:0x45c0
	ds_read_b64_tr_b16 v[118:119], v2 offset:0x67c0
	v_mfma_f32_16x16x32_bf16 v[12:15], v[48:51], v[120:123], v[12:15]
	ds_read_b64_tr_b16 v[120:121], v2 offset:0x1e0
	ds_read_b64_tr_b16 v[122:123], v2 offset:0x23e0
	v_mfma_f32_16x16x32_bf16 v[12:15], v[56:59], v[124:127], v[12:15]
	ds_read_b64_tr_b16 v[124:125], v2 offset:0x45e0
	ds_read_b64_tr_b16 v[126:127], v2 offset:0x67e0
	s_waitcnt lgkmcnt(8)
	v_mfma_f32_16x16x32_bf16 v[28:31], v[48:51], v[84:87], v[28:31]
	s_waitcnt lgkmcnt(0)
	v_mfma_f32_16x16x32_bf16 v[36:39], v[48:51], v[104:107], v[36:39]
	v_mfma_f32_16x16x32_bf16 v[28:31], v[56:59], v[100:103], v[28:31]
	v_mfma_f32_16x16x32_bf16 v[36:39], v[56:59], v[108:111], v[36:39]
	v_mfma_f32_16x16x32_bf16 v[16:19], v[48:51], v[112:115], v[16:19]
	v_mfma_f32_16x16x32_bf16 v[8:11], v[48:51], v[120:123], v[8:11]
	v_mfma_f32_16x16x32_bf16 v[16:19], v[56:59], v[116:119], v[16:19]
	v_mfma_f32_16x16x32_bf16 v[8:11], v[56:59], v[124:127], v[8:11]
	s_setprio 0
.LBB0_496:
	s_setprio 0
	s_sub_i32 s1, s13, s14
	s_lshl_b32 s1, s1, 6
	v_cvt_f32_i32_e32 v2, s1
	s_waitcnt lgkmcnt(0)
	s_barrier
	s_or_b32 s4, s1, 63
	s_mov_b64 s[2:3], -1
	v_sub_f32_e32 v108, v5, v2
	v_add_f32_e32 v106, 0xc1800000, v108
	v_add_f32_e32 v104, 0xc2000000, v108
	v_add_f32_e32 v4, 0xc2400000, v108
	s_cmp_lt_i32 s4, s26
	v_add_f32_e32 v109, -1.0, v108
	v_add_f32_e32 v107, -1.0, v106
	v_add_f32_e32 v105, -1.0, v104
	v_add_f32_e32 v5, -1.0, v4
	s_cbranch_scc1 .LBB0_500
	v_pk_add_f32 v[56:57], v[106:107], -2.0 op_sel_hi:[1,0]
	v_and_b32_e32 v84, 0x7fffffff, v106
	v_and_b32_e32 v57, 0x7fffffff, v57
	v_and_b32_e32 v56, 0x7fffffff, v56
	v_and_b32_e32 v85, 0x7fffffff, v107
	v_pk_fma_f32 v[58:59], v[56:57], v[146:147], v[94:95] op_sel_hi:[1,0,1]
	v_pk_fma_f32 v[56:57], v[84:85], v[146:147], v[92:93] op_sel_hi:[1,0,1]
	v_pk_add_f32 v[84:85], v[104:105], -2.0 op_sel_hi:[1,0]
	v_and_b32_e32 v100, 0x7fffffff, v104
	v_and_b32_e32 v85, 0x7fffffff, v85
	v_and_b32_e32 v84, 0x7fffffff, v84
	v_and_b32_e32 v101, 0x7fffffff, v105
	v_pk_add_f32 v[48:49], v[108:109], -2.0 op_sel_hi:[1,0]
	v_pk_fma_f32 v[86:87], v[84:85], v[146:147], v[98:99] op_sel_hi:[1,0,1]
	v_pk_fma_f32 v[84:85], v[100:101], v[146:147], v[96:97] op_sel_hi:[1,0,1]
	v_pk_add_f32 v[100:101], v[4:5], -2.0 op_sel_hi:[1,0]
	s_sub_i32 s1, s12, s1
	v_and_b32_e32 v51, 0x7fffffff, v49
	v_and_b32_e32 v50, 0x7fffffff, v48
	v_and_b32_e32 v48, 0x7fffffff, v108
	v_and_b32_e32 v49, 0x7fffffff, v109
	v_and_b32_e32 v101, 0x7fffffff, v101
	v_and_b32_e32 v100, 0x7fffffff, v100
	v_and_b32_e32 v110, 0x7fffffff, v4
	v_and_b32_e32 v111, 0x7fffffff, v5
	v_pk_fma_f32 v[48:49], v[48:49], v[146:147], v[88:89] op_sel_hi:[1,0,1]
	v_pk_fma_f32 v[50:51], v[50:51], v[146:147], v[90:91] op_sel_hi:[1,0,1]
	v_pk_fma_f32 v[102:103], v[100:101], v[146:147], v[54:55] op_sel_hi:[1,0,1]
	s_cmp_lt_i32 s1, 64
	v_pk_fma_f32 v[100:101], v[110:111], v[146:147], v[52:53] op_sel_hi:[1,0,1]
	s_cbranch_scc0 .LBB0_499
	v_or_b32_e32 v2, 1, v216
	v_cmp_gt_i32_e64 s[42:43], s1, v2
	v_or_b32_e32 v2, 2, v216
	v_cmp_gt_i32_e64 s[44:45], s1, v2
	v_or_b32_e32 v2, 3, v216
	v_cmp_gt_i32_e64 s[46:47], s1, v2
	s_or_b64 s[44:45], s[46:47], s[44:45]
	v_cmp_gt_i32_e32 vcc, s1, v216
	s_or_b64 s[42:43], s[44:45], s[42:43]
	s_or_b64 vcc, s[42:43], vcc
	v_or_b32_e32 v2, 16, v216
	v_cndmask_b32_e32 v48, v202, v48, vcc
	v_cmp_gt_i32_e32 vcc, s1, v2
	v_or_b32_e32 v2, 17, v216
	v_cndmask_b32_e64 v49, v202, v49, s[42:43]
	v_cmp_gt_i32_e64 s[42:43], s1, v2
	v_or_b32_e32 v2, 18, v216
	v_cndmask_b32_e64 v50, v202, v50, s[44:45]
	v_cmp_gt_i32_e64 s[44:45], s1, v2
	v_or_b32_e32 v2, 19, v216
	v_cndmask_b32_e64 v51, v202, v51, s[46:47]
	v_cmp_gt_i32_e64 s[46:47], s1, v2
	s_or_b64 s[44:45], s[46:47], s[44:45]
	s_or_b64 s[42:43], s[44:45], s[42:43]
	s_or_b64 vcc, s[42:43], vcc
	v_or_b32_e32 v2, 32, v216
	v_cndmask_b32_e32 v56, v202, v56, vcc
	v_cmp_gt_i32_e32 vcc, s1, v2
	v_or_b32_e32 v2, 33, v216
	v_cndmask_b32_e64 v57, v202, v57, s[42:43]
	v_cmp_gt_i32_e64 s[42:43], s1, v2
	v_or_b32_e32 v2, 34, v216
	v_cndmask_b32_e64 v58, v202, v58, s[44:45]
	v_cmp_gt_i32_e64 s[44:45], s1, v2
	v_or_b32_e32 v2, 35, v216
	v_cndmask_b32_e64 v59, v202, v59, s[46:47]
	v_cmp_gt_i32_e64 s[46:47], s1, v2
	s_or_b64 s[44:45], s[46:47], s[44:45]
	s_or_b64 s[42:43], s[44:45], s[42:43]
	s_or_b64 vcc, s[42:43], vcc
	v_or_b32_e32 v2, 48, v216
	v_cndmask_b32_e32 v84, v202, v84, vcc
	v_cmp_gt_i32_e32 vcc, s1, v2
	v_or_b32_e32 v2, 49, v216
	v_cndmask_b32_e64 v85, v202, v85, s[42:43]
	v_cmp_gt_i32_e64 s[42:43], s1, v2
	v_or_b32_e32 v2, 50, v216
	v_cndmask_b32_e64 v86, v202, v86, s[44:45]
	v_cmp_gt_i32_e64 s[44:45], s1, v2
	v_or_b32_e32 v2, 51, v216
	v_cndmask_b32_e64 v87, v202, v87, s[46:47]
	v_cmp_gt_i32_e64 s[46:47], s1, v2
	s_or_b64 s[44:45], s[46:47], s[44:45]
	s_or_b64 s[42:43], s[44:45], s[42:43]
	s_or_b64 vcc, s[42:43], vcc
	v_cndmask_b32_e64 v103, v202, v103, s[46:47]
	v_cndmask_b32_e64 v102, v202, v102, s[44:45]
	v_cndmask_b32_e64 v101, v202, v101, s[42:43]
	v_cndmask_b32_e32 v100, v202, v100, vcc
